# v52 = v51 plus one s_nop 0 between each inserted s_addc_u32 and the DMA that reads that SGPR pair (8 sites)
# speedup vs baseline: 1.0052x; 1.0007x over previous
; #define PG8_STAGE(bufoff, gbase, voff) do { _Pragma("unroll") for (int _i = 0; _i < 2; ++_i) \
;         __builtin_amdgcn_global_load_lds((const unsigned*)((const char*)(gbase) + (voff)[_i]), (LAS unsigned*)(lds + (bufoff) + ldsw + _i * 8192), 16, 0, 0); } while (0)
; #define PG8_LDA(dst, b, h) do { _Pragma("unroll") for (int m = 0; m < 4; ++m) _Pragma("unroll") for (int k = 0; k < 2; ++k) dst[m][k] = *(const LAS bf16x8*)(lds + PG8_SA(b, h) + aoffk[k] + m * 2048); } while (0)
; #define PG8_LDB(dst, b, h) do { _Pragma("unroll") for (int n = 0; n < 2; ++n) _Pragma("unroll") for (int k = 0; k < 2; ++k) dst[n][k] = *(const LAS bf16x8*)(lds + PG8_SB(b, h) + boffk[k] + n * 2048); } while (0)
; #define PG8_WAIT_V(n) asm volatile("s_waitcnt vmcnt(" #n ")" ::: "memory")
; #define PG8_WAIT_L(n) asm volatile("s_waitcnt lgkmcnt(" #n ")" ::: "memory")
; #define PG8_BAR __builtin_amdgcn_s_barrier()
; #define PG8_SCHED __builtin_amdgcn_sched_barrier(0)
; template <class Epi, class Sched, class GemmT>
; __device__ __forceinline__ void gemm_phase(LAS unsigned char* lds, const GemmT& g, const Sched& S, const Epi& E, const int wid) {
;     ...
;                 PG8_LDB(B0, 0, 0); PG8_LDB(B1, 0, 1); PG8_SCHED; PG8_LDA(At, 0, 0); PG8_STAGE(PG8_SA(1, 1), a1 + hstepA, voffA);
;                 PG8_WAIT_V(8); PG8_WAIT_L(0); PG8_BAR; PG8_MMA(0, 0, At, B0); PG8_MMA(0, 1, At, B1); PG8_BAR; PG8_SCHED;
;                 PG8_LDA(At, 0, 1); PG8_STAGE(PG8_SB(0, 0), b2, vB2); PG8_STAGE(PG8_SB(0, 1), b2 + hB2, vB2); PG8_STAGE(PG8_SA(0, 0), a2, vA2);
;                 PG8_WAIT_V(8); PG8_WAIT_L(0); PG8_BAR; PG8_MMA(1, 0, At, B0); PG8_MMA(1, 1, At, B1); PG8_BAR; PG8_SCHED;
.LBB0_361:
	ds_read_b128 v[24:27], v186
	ds_read_b128 v[28:31], v187
	ds_read_b128 v[16:19], v188
	ds_read_b128 v[20:23], v189
	ds_read_b128 v[8:11], v190
	ds_read_b128 v[12:15], v191
	ds_read_b128 v[0:3], v192
	ds_read_b128 v[4:7], v193
	s_add_u32 s41, s56, 0xfff80080
	s_addc_u32 s48, s57, -1
	s_cmp_eq_u32 s40, 28
	s_cselect_b32 s83, s43, s48
	s_cselect_b32 s82, s42, s41
	s_cselect_b32 s59, s37, s39
	s_cselect_b32 s58, s36, s38
	s_add_i32 m0, s12, 0xc000
	ds_read_b128 v[174:177], v194
	ds_read_b128 v[204:207], v194 offset:2048
	ds_read_b128 v[178:181], v195
	ds_read_b128 v[208:211], v195 offset:2048
	ds_read_b128 v[212:215], v194 offset:4096
	ds_read_b128 v[220:223], v194 offset:6144
	ds_read_b128 v[216:219], v195 offset:4096
	ds_read_b128 v[224:227], v195 offset:6144
	global_load_lds_dwordx4 v160, s[56:57]
	s_add_i32 m0, s12, 0xe000
	s_nop 0
	global_load_lds_dwordx4 v164, s[56:57]
	s_waitcnt vmcnt(8)
	s_waitcnt lgkmcnt(0)
	s_waitcnt lgkmcnt(0)
	v_mfma_scale_f32_16x16x128_f8f6f4 v[156:159], v[24:31], v[174:181], v[156:159], v196, v196 op_sel_hi:[0,0,0]
	v_mfma_scale_f32_16x16x128_f8f6f4 v[152:155], v[16:23], v[174:181], v[152:155], v196, v196 op_sel_hi:[0,0,0]
	s_barrier
	s_setprio 3
	v_mfma_scale_f32_16x16x128_f8f6f4 v[136:139], v[16:23], v[204:211], v[136:139], v196, v196 op_sel_hi:[0,0,0]
	v_mfma_scale_f32_16x16x128_f8f6f4 v[140:143], v[24:31], v[204:211], v[140:143], v196, v196 op_sel_hi:[0,0,0]
	v_mfma_scale_f32_16x16x128_f8f6f4 v[124:127], v[24:31], v[212:219], v[124:127], v196, v196 op_sel_hi:[0,0,0]
	v_mfma_scale_f32_16x16x128_f8f6f4 v[120:123], v[16:23], v[212:219], v[120:123], v196, v196 op_sel_hi:[0,0,0]
	v_mfma_scale_f32_16x16x128_f8f6f4 v[104:107], v[16:23], v[220:227], v[104:107], v196, v196 op_sel_hi:[0,0,0]
	v_mfma_scale_f32_16x16x128_f8f6f4 v[108:111], v[24:31], v[220:227], v[108:111], v196, v196 op_sel_hi:[0,0,0]
	s_setprio 0
	s_setprio 3
	v_mfma_scale_f32_16x16x128_f8f6f4 v[148:151], v[8:15], v[174:181], v[148:151], v196, v196 op_sel_hi:[0,0,0]
	v_mfma_scale_f32_16x16x128_f8f6f4 v[144:147], v[0:7], v[174:181], v[144:147], v196, v196 op_sel_hi:[0,0,0]
	v_mfma_scale_f32_16x16x128_f8f6f4 v[128:131], v[0:7], v[204:211], v[128:131], v196, v196 op_sel_hi:[0,0,0]
	v_mfma_scale_f32_16x16x128_f8f6f4 v[132:135], v[8:15], v[204:211], v[132:135], v196, v196 op_sel_hi:[0,0,0]
	v_mfma_scale_f32_16x16x128_f8f6f4 v[116:119], v[8:15], v[212:219], v[116:119], v196, v196 op_sel_hi:[0,0,0]
	v_mfma_scale_f32_16x16x128_f8f6f4 v[112:115], v[0:7], v[212:219], v[112:115], v196, v196 op_sel_hi:[0,0,0]
	v_mfma_scale_f32_16x16x128_f8f6f4 v[96:99], v[0:7], v[220:227], v[96:99], v196, v196 op_sel_hi:[0,0,0]
	v_mfma_scale_f32_16x16x128_f8f6f4 v[100:103], v[8:15], v[220:227], v[100:103], v196, v196 op_sel_hi:[0,0,0]
	s_setprio 0
	s_barrier
	s_add_i32 s41, s64, s68
	s_mov_b32 m0, s41
	ds_read_b128 v[204:207], v194 offset:16384
	ds_read_b128 v[212:215], v194 offset:18432
	ds_read_b128 v[208:211], v195 offset:16384
	ds_read_b128 v[216:219], v195 offset:18432
	ds_read_b128 v[220:223], v194 offset:20480
	ds_read_b128 v[230:233], v194 offset:22528
	ds_read_b128 v[224:227], v195 offset:20480
	ds_read_b128 v[234:237], v195 offset:22528
	global_load_lds_dwordx4 v162, s[58:59]
	s_add_i32 m0, s41, 0x2000
	s_add_u32 s50, s58, 0x80000
	s_addc_u32 s51, s59, 0
	s_add_i32 s41, s65, s68
	global_load_lds_dwordx4 v166, s[58:59]
	s_mov_b32 m0, s41
	s_nop 0
	global_load_lds_dwordx4 v162, s[50:51]
	s_add_i32 m0, s41, 0x2000
	s_nop 0
	global_load_lds_dwordx4 v166, s[50:51]
	s_mov_b32 m0, s12
	s_nop 0
	global_load_lds_dwordx4 v160, s[82:83]
	s_mov_b32 m0, s13
	s_nop 0
	global_load_lds_dwordx4 v164, s[82:83]
	s_waitcnt vmcnt(8)
	s_waitcnt lgkmcnt(0)
	s_waitcnt lgkmcnt(0)
	v_mfma_scale_f32_16x16x128_f8f6f4 v[84:87], v[24:31], v[204:211], v[84:87], v196, v196 op_sel_hi:[0,0,0]
	v_mfma_scale_f32_16x16x128_f8f6f4 v[80:83], v[16:23], v[204:211], v[80:83], v196, v196 op_sel_hi:[0,0,0]
	s_barrier
	s_setprio 3
	v_mfma_scale_f32_16x16x128_f8f6f4 v[64:67], v[16:23], v[212:219], v[64:67], v196, v196 op_sel_hi:[0,0,0]
	v_mfma_scale_f32_16x16x128_f8f6f4 v[68:71], v[24:31], v[212:219], v[68:71], v196, v196 op_sel_hi:[0,0,0]
	v_mfma_scale_f32_16x16x128_f8f6f4 v[52:55], v[24:31], v[220:227], v[52:55], v196, v196 op_sel_hi:[0,0,0]
	v_mfma_scale_f32_16x16x128_f8f6f4 v[48:51], v[16:23], v[220:227], v[48:51], v196, v196 op_sel_hi:[0,0,0]
	v_mfma_scale_f32_16x16x128_f8f6f4 v[32:35], v[16:23], v[230:237], v[32:35], v196, v196 op_sel_hi:[0,0,0]
	v_mfma_scale_f32_16x16x128_f8f6f4 v[36:39], v[24:31], v[230:237], v[36:39], v196, v196 op_sel_hi:[0,0,0]
	s_setprio 0
	s_setprio 3
	v_mfma_scale_f32_16x16x128_f8f6f4 v[92:95], v[8:15], v[204:211], v[92:95], v196, v196 op_sel_hi:[0,0,0]
	v_mfma_scale_f32_16x16x128_f8f6f4 v[88:91], v[0:7], v[204:211], v[88:91], v196, v196 op_sel_hi:[0,0,0]
	v_mfma_scale_f32_16x16x128_f8f6f4 v[72:75], v[0:7], v[212:219], v[72:75], v196, v196 op_sel_hi:[0,0,0]
	v_mfma_scale_f32_16x16x128_f8f6f4 v[76:79], v[8:15], v[212:219], v[76:79], v196, v196 op_sel_hi:[0,0,0]
	v_mfma_scale_f32_16x16x128_f8f6f4 v[60:63], v[8:15], v[220:227], v[60:63], v196, v196 op_sel_hi:[0,0,0]
	v_mfma_scale_f32_16x16x128_f8f6f4 v[56:59], v[0:7], v[220:227], v[56:59], v196, v196 op_sel_hi:[0,0,0]
	v_mfma_scale_f32_16x16x128_f8f6f4 v[40:43], v[0:7], v[230:237], v[40:43], v196, v196 op_sel_hi:[0,0,0]
	v_mfma_scale_f32_16x16x128_f8f6f4 v[44:47], v[8:15], v[230:237], v[44:47], v196, v196 op_sel_hi:[0,0,0]
	s_setprio 0
	s_barrier
; #define PG8_STAGE(bufoff, gbase, voff) do { _Pragma("unroll") for (int _i = 0; _i < 2; ++_i) \
;         __builtin_amdgcn_global_load_lds((const unsigned*)((const char*)(gbase) + (voff)[_i]), (LAS unsigned*)(lds + (bufoff) + ldsw + _i * 8192), 16, 0, 0); } while (0)
; #define PG8_LDA(dst, b, h) do { _Pragma("unroll") for (int m = 0; m < 4; ++m) _Pragma("unroll") for (int k = 0; k < 2; ++k) dst[m][k] = *(const LAS bf16x8*)(lds + PG8_SA(b, h) + aoffk[k] + m * 2048); } while (0)
; #define PG8_LDB(dst, b, h) do { _Pragma("unroll") for (int n = 0; n < 2; ++n) _Pragma("unroll") for (int k = 0; k < 2; ++k) dst[n][k] = *(const LAS bf16x8*)(lds + PG8_SB(b, h) + boffk[k] + n * 2048); } while (0)
; #define PG8_WAIT_V(n) asm volatile("s_waitcnt vmcnt(" #n ")" ::: "memory")
; #define PG8_WAIT_L(n) asm volatile("s_waitcnt lgkmcnt(" #n ")" ::: "memory")
; #define PG8_BAR __builtin_amdgcn_s_barrier()
; #define PG8_SCHED __builtin_amdgcn_sched_barrier(0)
; template <class Epi, class Sched, class GemmT>
; __device__ __forceinline__ void gemm_phase(LAS unsigned char* lds, const GemmT& g, const Sched& S, const Epi& E, const int wid) {
;     ...
;                 PG8_LDB(B0, 1, 0); PG8_LDB(B1, 1, 1); PG8_SCHED; PG8_LDA(At, 1, 0); PG8_STAGE(PG8_SA(0, 1), a2 + hA2, vA2);
;                 PG8_WAIT_V(8); PG8_WAIT_L(0); PG8_BAR; PG8_MMA(0, 0, At, B0); PG8_MMA(0, 1, At, B1); PG8_BAR; PG8_SCHED;
;                 PG8_LDA(At, 1, 1); PG8_STAGE(PG8_SB(1, 0), b3, vB2); PG8_STAGE(PG8_SB(1, 1), b3 + hB2, vB2); PG8_STAGE(PG8_SA(1, 0), a3, vA2);
;                 PG8_WAIT_V(8); PG8_WAIT_L(0); PG8_BAR; PG8_MMA(1, 0, At, B0); PG8_MMA(1, 1, At, B1); PG8_BAR; PG8_SCHED;
;             }
	s_add_i32 s41, 0, 0x18000
	s_add_i32 s48, 0, 0x1c000
	v_add_u32_e32 v0, s41, v184
	v_add_u32_e32 v4, s41, v185
	v_add_u32_e32 v16, s48, v184
	v_add_u32_e32 v20, s48, v185
	ds_read_b128 v[0:3], v0
	ds_read_b128 v[4:7], v4
	ds_read_b128 v[8:11], v197
	ds_read_b128 v[12:15], v198
	ds_read_b128 v[16:19], v16
	ds_read_b128 v[20:23], v20
	ds_read_b128 v[24:27], v199
	ds_read_b128 v[28:31], v200
	s_add_u32 s50, s82, 0x80000
	s_addc_u32 s51, s83, 0
	s_mov_b32 m0, s15
	ds_read_b128 v[204:207], v194 offset:32768
	ds_read_b128 v[212:215], v194 offset:34816
	ds_read_b128 v[208:211], v195 offset:32768
	ds_read_b128 v[216:219], v195 offset:34816
	ds_read_b128 v[220:223], v194 offset:36864
	ds_read_b128 v[230:233], v194 offset:38912
	ds_read_b128 v[224:227], v195 offset:36864
	ds_read_b128 v[234:237], v195 offset:38912
	global_load_lds_dwordx4 v160, s[50:51]
	s_mov_b32 m0, s21
	s_nop 0
	global_load_lds_dwordx4 v164, s[50:51]
	s_waitcnt vmcnt(8)
	s_waitcnt lgkmcnt(0)
	s_waitcnt lgkmcnt(0)
	v_mfma_scale_f32_16x16x128_f8f6f4 v[156:159], v[0:7], v[204:211], v[156:159], v196, v196 op_sel_hi:[0,0,0]
	v_mfma_scale_f32_16x16x128_f8f6f4 v[152:155], v[8:15], v[204:211], v[152:155], v196, v196 op_sel_hi:[0,0,0]
	s_barrier
	s_setprio 3
	v_mfma_scale_f32_16x16x128_f8f6f4 v[136:139], v[8:15], v[212:219], v[136:139], v196, v196 op_sel_hi:[0,0,0]
	v_mfma_scale_f32_16x16x128_f8f6f4 v[140:143], v[0:7], v[212:219], v[140:143], v196, v196 op_sel_hi:[0,0,0]
	v_mfma_scale_f32_16x16x128_f8f6f4 v[124:127], v[0:7], v[220:227], v[124:127], v196, v196 op_sel_hi:[0,0,0]
	v_mfma_scale_f32_16x16x128_f8f6f4 v[120:123], v[8:15], v[220:227], v[120:123], v196, v196 op_sel_hi:[0,0,0]
	v_mfma_scale_f32_16x16x128_f8f6f4 v[104:107], v[8:15], v[230:237], v[104:107], v196, v196 op_sel_hi:[0,0,0]
	v_mfma_scale_f32_16x16x128_f8f6f4 v[108:111], v[0:7], v[230:237], v[108:111], v196, v196 op_sel_hi:[0,0,0]
	s_setprio 0
	s_setprio 3
	v_mfma_scale_f32_16x16x128_f8f6f4 v[148:151], v[16:23], v[204:211], v[148:151], v196, v196 op_sel_hi:[0,0,0]
	v_mfma_scale_f32_16x16x128_f8f6f4 v[144:147], v[24:31], v[204:211], v[144:147], v196, v196 op_sel_hi:[0,0,0]
	v_mfma_scale_f32_16x16x128_f8f6f4 v[128:131], v[24:31], v[212:219], v[128:131], v196, v196 op_sel_hi:[0,0,0]
	v_mfma_scale_f32_16x16x128_f8f6f4 v[132:135], v[16:23], v[212:219], v[132:135], v196, v196 op_sel_hi:[0,0,0]
	v_mfma_scale_f32_16x16x128_f8f6f4 v[116:119], v[16:23], v[220:227], v[116:119], v196, v196 op_sel_hi:[0,0,0]
	v_mfma_scale_f32_16x16x128_f8f6f4 v[112:115], v[24:31], v[220:227], v[112:115], v196, v196 op_sel_hi:[0,0,0]
	v_mfma_scale_f32_16x16x128_f8f6f4 v[96:99], v[24:31], v[230:237], v[96:99], v196, v196 op_sel_hi:[0,0,0]
	v_mfma_scale_f32_16x16x128_f8f6f4 v[100:103], v[16:23], v[230:237], v[100:103], v196, v196 op_sel_hi:[0,0,0]
	s_setprio 0
	s_barrier
	s_add_i32 s41, s41, s68
	s_mov_b32 m0, s41
	ds_read_b128 v[204:207], v194 offset:49152
	ds_read_b128 v[212:215], v194 offset:51200
	ds_read_b128 v[208:211], v195 offset:49152
	ds_read_b128 v[216:219], v195 offset:51200
	ds_read_b128 v[220:223], v194 offset:53248
	ds_read_b128 v[230:233], v194 offset:55296
	ds_read_b128 v[224:227], v195 offset:53248
	ds_read_b128 v[234:237], v195 offset:55296
	s_add_u32 s98, s58, 0x80
	s_addc_u32 s99, s59, 0
	s_nop 0
	global_load_lds_dwordx4 v162, s[98:99]
	s_add_i32 m0, s41, 0x2000
	s_add_u32 s50, s58, 0x80080
	s_addc_u32 s51, s59, 0
	s_add_i32 s41, s48, s68
	global_load_lds_dwordx4 v166, s[98:99]
	s_mov_b32 m0, s41
	s_nop 0
	global_load_lds_dwordx4 v162, s[50:51]
	s_add_i32 m0, s41, 0x2000
	s_nop 0
	global_load_lds_dwordx4 v166, s[50:51]
	s_mov_b32 m0, s35
	s_nop 0
	s_add_u32 s98, s82, 0x80
	s_addc_u32 s99, s83, 0
	s_nop 0
	global_load_lds_dwordx4 v160, s[98:99]
	s_mov_b32 m0, s53
	s_nop 0
	global_load_lds_dwordx4 v164, s[98:99]
	s_waitcnt vmcnt(8)
	s_waitcnt lgkmcnt(0)
	s_waitcnt lgkmcnt(0)
	v_mfma_scale_f32_16x16x128_f8f6f4 v[84:87], v[0:7], v[204:211], v[84:87], v196, v196 op_sel_hi:[0,0,0]
	v_mfma_scale_f32_16x16x128_f8f6f4 v[80:83], v[8:15], v[204:211], v[80:83], v196, v196 op_sel_hi:[0,0,0]
	s_barrier
	s_setprio 3
	v_mfma_scale_f32_16x16x128_f8f6f4 v[64:67], v[8:15], v[212:219], v[64:67], v196, v196 op_sel_hi:[0,0,0]
	v_mfma_scale_f32_16x16x128_f8f6f4 v[68:71], v[0:7], v[212:219], v[68:71], v196, v196 op_sel_hi:[0,0,0]
	v_mfma_scale_f32_16x16x128_f8f6f4 v[52:55], v[0:7], v[220:227], v[52:55], v196, v196 op_sel_hi:[0,0,0]
	v_mfma_scale_f32_16x16x128_f8f6f4 v[48:51], v[8:15], v[220:227], v[48:51], v196, v196 op_sel_hi:[0,0,0]
	v_mfma_scale_f32_16x16x128_f8f6f4 v[32:35], v[8:15], v[230:237], v[32:35], v196, v196 op_sel_hi:[0,0,0]
	v_mfma_scale_f32_16x16x128_f8f6f4 v[36:39], v[0:7], v[230:237], v[36:39], v196, v196 op_sel_hi:[0,0,0]
	s_setprio 0
	s_setprio 3
	v_mfma_scale_f32_16x16x128_f8f6f4 v[92:95], v[16:23], v[204:211], v[92:95], v196, v196 op_sel_hi:[0,0,0]
	v_mfma_scale_f32_16x16x128_f8f6f4 v[88:91], v[24:31], v[204:211], v[88:91], v196, v196 op_sel_hi:[0,0,0]
	v_mfma_scale_f32_16x16x128_f8f6f4 v[72:75], v[24:31], v[212:219], v[72:75], v196, v196 op_sel_hi:[0,0,0]
	v_mfma_scale_f32_16x16x128_f8f6f4 v[76:79], v[16:23], v[212:219], v[76:79], v196, v196 op_sel_hi:[0,0,0]
	v_mfma_scale_f32_16x16x128_f8f6f4 v[60:63], v[16:23], v[220:227], v[60:63], v196, v196 op_sel_hi:[0,0,0]
	v_mfma_scale_f32_16x16x128_f8f6f4 v[56:59], v[24:31], v[220:227], v[56:59], v196, v196 op_sel_hi:[0,0,0]
	v_mfma_scale_f32_16x16x128_f8f6f4 v[40:43], v[24:31], v[230:237], v[40:43], v196, v196 op_sel_hi:[0,0,0]
	v_mfma_scale_f32_16x16x128_f8f6f4 v[44:47], v[16:23], v[230:237], v[44:47], v196, v196 op_sel_hi:[0,0,0]
	s_setprio 0
	s_barrier
	s_add_i32 s40, s40, 2
	s_add_u32 s56, s56, 0x100
	s_addc_u32 s57, s57, 0
	s_add_u32 s38, s38, 0x100
	s_addc_u32 s39, s39, 0
	s_cmp_gt_u32 s40, 29
	s_cbranch_scc0 .LBB0_361
	s_and_b64 vcc, exec, s[16:17]
	s_cbranch_vccz .LBB0_364
	s_barrier

; #define PG8_STAGE(bufoff, gbase, voff) do { _Pragma("unroll") for (int _i = 0; _i < 2; ++_i) \
;         __builtin_amdgcn_global_load_lds((const unsigned*)((const char*)(gbase) + (voff)[_i]), (LAS unsigned*)(lds + (bufoff) + ldsw + _i * 8192), 16, 0, 0); } while (0)
; #define PG8_LDA(dst, b, h) do { _Pragma("unroll") for (int m = 0; m < 4; ++m) _Pragma("unroll") for (int k = 0; k < 2; ++k) dst[m][k] = *(const LAS bf16x8*)(lds + PG8_SA(b, h) + aoffk[k] + m * 2048); } while (0)
; #define PG8_LDB(dst, b, h) do { _Pragma("unroll") for (int n = 0; n < 2; ++n) _Pragma("unroll") for (int k = 0; k < 2; ++k) dst[n][k] = *(const LAS bf16x8*)(lds + PG8_SB(b, h) + boffk[k] + n * 2048); } while (0)
; #define PG8_WAIT_V(n) asm volatile("s_waitcnt vmcnt(" #n ")" ::: "memory")
; #define PG8_WAIT_L(n) asm volatile("s_waitcnt lgkmcnt(" #n ")" ::: "memory")
; #define PG8_BAR __builtin_amdgcn_s_barrier()
; #define PG8_SCHED __builtin_amdgcn_sched_barrier(0)
; template <class Epi, class Sched, class GemmT>
; __device__ __forceinline__ void gemm_phase(LAS unsigned char* lds, const GemmT& g, const Sched& S, const Epi& E, const int wid) {
;     ...
;                 PG8_LDB(B0, 0, 0); PG8_LDB(B1, 0, 1); PG8_SCHED; PG8_LDA(At, 0, 0); PG8_STAGE(PG8_SA(1, 1), a1 + hstepA, voffA);
;                 PG8_WAIT_V(8); PG8_WAIT_L(0); PG8_BAR; PG8_MMA(0, 0, At, B0); PG8_MMA(0, 1, At, B1); PG8_BAR; PG8_SCHED;
;                 PG8_LDA(At, 0, 1); PG8_STAGE(PG8_SB(0, 0), b2, vB2); PG8_STAGE(PG8_SB(0, 1), b2 + hB2, vB2); PG8_STAGE(PG8_SA(0, 0), a2, vA2);
;                 PG8_WAIT_V(8); PG8_WAIT_L(0); PG8_BAR; PG8_MMA(1, 0, At, B0); PG8_MMA(1, 1, At, B1); PG8_BAR; PG8_SCHED;
.LBB0_417:
	ds_read_b128 v[140:143], v192
	ds_read_b128 v[144:147], v193
	ds_read_b128 v[148:151], v194
	ds_read_b128 v[152:155], v195
	ds_read_b128 v[156:159], v196
	ds_read_b128 v[160:163], v197
	ds_read_b128 v[164:167], v198
	ds_read_b128 v[168:171], v199
	s_add_u32 s39, s84, 0xfff00080
	s_addc_u32 s40, s85, -1
	s_cmp_eq_u32 s38, 60
	s_cselect_b32 s87, s57, s40
	s_cselect_b32 s86, s56, s39
	s_cselect_b32 s71, s16, s37
	s_cselect_b32 s70, s5, s36
	s_add_i32 m0, s9, 0xc000
	ds_read_b128 v[172:175], v200
	ds_read_b128 v[208:211], v200 offset:2048
	ds_read_b128 v[212:215], v201
	ds_read_b128 v[216:219], v201 offset:2048
	ds_read_b128 v[220:223], v200 offset:4096
	ds_read_b128 v[224:227], v200 offset:6144
	ds_read_b128 v[230:233], v201 offset:4096
	ds_read_b128 v[234:237], v201 offset:6144
	global_load_lds_dwordx4 v128, s[84:85]
	s_add_i32 m0, s9, 0xe000
	s_nop 0
	global_load_lds_dwordx4 v132, s[84:85]
	s_waitcnt vmcnt(8)
	s_waitcnt lgkmcnt(0)
	s_waitcnt lgkmcnt(0)
	v_mfma_f32_16x16x32_bf16 v[124:127], v[140:143], v[172:175], v[124:127]
	v_mfma_f32_16x16x32_bf16 v[124:127], v[144:147], v[212:215], v[124:127]
	v_mfma_f32_16x16x32_bf16 v[120:123], v[152:155], v[212:215], v[120:123]
	v_mfma_f32_16x16x32_bf16 v[120:123], v[148:151], v[172:175], v[120:123]
	s_barrier
	s_setprio 3
	v_mfma_f32_16x16x32_bf16 v[112:115], v[148:151], v[208:211], v[112:115]
	v_mfma_f32_16x16x32_bf16 v[112:115], v[152:155], v[216:219], v[112:115]
	v_mfma_f32_16x16x32_bf16 v[116:119], v[144:147], v[216:219], v[116:119]
	v_mfma_f32_16x16x32_bf16 v[116:119], v[140:143], v[208:211], v[116:119]
	v_mfma_f32_16x16x32_bf16 v[100:103], v[140:143], v[220:223], v[100:103]
	v_mfma_f32_16x16x32_bf16 v[100:103], v[144:147], v[230:233], v[100:103]
	v_mfma_f32_16x16x32_bf16 v[96:99], v[152:155], v[230:233], v[96:99]
	v_mfma_f32_16x16x32_bf16 v[96:99], v[148:151], v[220:223], v[96:99]
	v_mfma_f32_16x16x32_bf16 v[76:79], v[148:151], v[224:227], v[76:79]
	v_mfma_f32_16x16x32_bf16 v[76:79], v[152:155], v[234:237], v[76:79]
	v_mfma_f32_16x16x32_bf16 v[84:87], v[144:147], v[234:237], v[84:87]
	v_mfma_f32_16x16x32_bf16 v[84:87], v[140:143], v[224:227], v[84:87]
	s_setprio 0
	s_setprio 3
	v_mfma_f32_16x16x32_bf16 v[108:111], v[156:159], v[172:175], v[108:111]
	v_mfma_f32_16x16x32_bf16 v[108:111], v[160:163], v[212:215], v[108:111]
	v_mfma_f32_16x16x32_bf16 v[104:107], v[168:171], v[212:215], v[104:107]
	v_mfma_f32_16x16x32_bf16 v[104:107], v[164:167], v[172:175], v[104:107]
	v_mfma_f32_16x16x32_bf16 v[88:91], v[164:167], v[208:211], v[88:91]
	v_mfma_f32_16x16x32_bf16 v[88:91], v[168:171], v[216:219], v[88:91]
	v_mfma_f32_16x16x32_bf16 v[92:95], v[160:163], v[216:219], v[92:95]
	v_mfma_f32_16x16x32_bf16 v[92:95], v[156:159], v[208:211], v[92:95]
	v_mfma_f32_16x16x32_bf16 v[68:71], v[156:159], v[220:223], v[68:71]
	v_mfma_f32_16x16x32_bf16 v[68:71], v[160:163], v[230:233], v[68:71]
	v_mfma_f32_16x16x32_bf16 v[64:67], v[168:171], v[230:233], v[64:67]
	v_mfma_f32_16x16x32_bf16 v[64:67], v[164:167], v[220:223], v[64:67]
	v_mfma_f32_16x16x32_bf16 v[40:43], v[164:167], v[224:227], v[40:43]
	v_mfma_f32_16x16x32_bf16 v[40:43], v[168:171], v[234:237], v[40:43]
	v_mfma_f32_16x16x32_bf16 v[48:51], v[160:163], v[234:237], v[48:51]
	v_mfma_f32_16x16x32_bf16 v[48:51], v[156:159], v[224:227], v[48:51]
	s_setprio 0
	s_barrier
	s_add_i32 s39, s35, s68
	s_mov_b32 m0, s39
	ds_read_b128 v[172:175], v200 offset:16384
	ds_read_b128 v[208:211], v200 offset:18432
	ds_read_b128 v[212:215], v201 offset:16384
	ds_read_b128 v[216:219], v201 offset:18432
	ds_read_b128 v[220:223], v200 offset:20480
	ds_read_b128 v[224:227], v200 offset:22528
	ds_read_b128 v[230:233], v201 offset:20480
	ds_read_b128 v[234:237], v201 offset:22528
	global_load_lds_dwordx4 v130, s[70:71]
	s_add_i32 m0, s39, 0x2000
	s_add_u32 s40, s70, 0x100000
	s_addc_u32 s41, s71, 0
	s_add_i32 s39, s69, s68
	global_load_lds_dwordx4 v134, s[70:71]
	s_mov_b32 m0, s39
	s_nop 0
	global_load_lds_dwordx4 v130, s[40:41]
	s_add_i32 m0, s39, 0x2000
	s_nop 0
	global_load_lds_dwordx4 v134, s[40:41]
	s_mov_b32 m0, s9
	s_nop 0
	global_load_lds_dwordx4 v128, s[86:87]
	s_mov_b32 m0, s29
	s_nop 0
	global_load_lds_dwordx4 v132, s[86:87]
	s_waitcnt vmcnt(8)
	s_waitcnt lgkmcnt(0)
	s_waitcnt lgkmcnt(0)
	v_mfma_f32_16x16x32_bf16 v[28:31], v[140:143], v[172:175], v[28:31]
	v_mfma_f32_16x16x32_bf16 v[28:31], v[144:147], v[212:215], v[28:31]
	v_mfma_f32_16x16x32_bf16 v[24:27], v[152:155], v[212:215], v[24:27]
	v_mfma_f32_16x16x32_bf16 v[24:27], v[148:151], v[172:175], v[24:27]
	s_barrier
	s_setprio 3
	v_mfma_f32_16x16x32_bf16 v[16:19], v[148:151], v[208:211], v[16:19]
	v_mfma_f32_16x16x32_bf16 v[16:19], v[152:155], v[216:219], v[16:19]
	v_mfma_f32_16x16x32_bf16 v[20:23], v[144:147], v[216:219], v[20:23]
	v_mfma_f32_16x16x32_bf16 v[20:23], v[140:143], v[208:211], v[20:23]
	v_mfma_f32_16x16x32_bf16 v[12:15], v[140:143], v[220:223], v[12:15]
	v_mfma_f32_16x16x32_bf16 v[12:15], v[144:147], v[230:233], v[12:15]
	v_mfma_f32_16x16x32_bf16 v[8:11], v[152:155], v[230:233], v[8:11]
	v_mfma_f32_16x16x32_bf16 v[8:11], v[148:151], v[220:223], v[8:11]
	v_mfma_f32_16x16x32_bf16 v[0:3], v[148:151], v[224:227], v[0:3]
	v_mfma_f32_16x16x32_bf16 v[0:3], v[152:155], v[234:237], v[0:3]
	v_mfma_f32_16x16x32_bf16 v[4:7], v[144:147], v[234:237], v[4:7]
	v_mfma_f32_16x16x32_bf16 v[4:7], v[140:143], v[224:227], v[4:7]
	s_setprio 0
	s_setprio 3
	v_mfma_f32_16x16x32_bf16 v[80:83], v[156:159], v[172:175], v[80:83]
	v_mfma_f32_16x16x32_bf16 v[80:83], v[160:163], v[212:215], v[80:83]
	v_mfma_f32_16x16x32_bf16 v[72:75], v[168:171], v[212:215], v[72:75]
	v_mfma_f32_16x16x32_bf16 v[72:75], v[164:167], v[172:175], v[72:75]
	v_mfma_f32_16x16x32_bf16 v[56:59], v[164:167], v[208:211], v[56:59]
	v_mfma_f32_16x16x32_bf16 v[56:59], v[168:171], v[216:219], v[56:59]
	v_mfma_f32_16x16x32_bf16 v[60:63], v[160:163], v[216:219], v[60:63]
	v_mfma_f32_16x16x32_bf16 v[60:63], v[156:159], v[208:211], v[60:63]
	v_mfma_f32_16x16x32_bf16 v[52:55], v[156:159], v[220:223], v[52:55]
	v_mfma_f32_16x16x32_bf16 v[52:55], v[160:163], v[230:233], v[52:55]
	v_mfma_f32_16x16x32_bf16 v[44:47], v[168:171], v[230:233], v[44:47]
	v_mfma_f32_16x16x32_bf16 v[44:47], v[164:167], v[220:223], v[44:47]
	v_mfma_f32_16x16x32_bf16 v[32:35], v[164:167], v[224:227], v[32:35]
	v_mfma_f32_16x16x32_bf16 v[32:35], v[168:171], v[234:237], v[32:35]
	v_mfma_f32_16x16x32_bf16 v[36:39], v[160:163], v[234:237], v[36:39]
	v_mfma_f32_16x16x32_bf16 v[36:39], v[156:159], v[224:227], v[36:39]
	s_setprio 0
	s_barrier
; #define PG8_STAGE(bufoff, gbase, voff) do { _Pragma("unroll") for (int _i = 0; _i < 2; ++_i) \
;         __builtin_amdgcn_global_load_lds((const unsigned*)((const char*)(gbase) + (voff)[_i]), (LAS unsigned*)(lds + (bufoff) + ldsw + _i * 8192), 16, 0, 0); } while (0)
; #define PG8_LDA(dst, b, h) do { _Pragma("unroll") for (int m = 0; m < 4; ++m) _Pragma("unroll") for (int k = 0; k < 2; ++k) dst[m][k] = *(const LAS bf16x8*)(lds + PG8_SA(b, h) + aoffk[k] + m * 2048); } while (0)
; #define PG8_LDB(dst, b, h) do { _Pragma("unroll") for (int n = 0; n < 2; ++n) _Pragma("unroll") for (int k = 0; k < 2; ++k) dst[n][k] = *(const LAS bf16x8*)(lds + PG8_SB(b, h) + boffk[k] + n * 2048); } while (0)
; #define PG8_WAIT_V(n) asm volatile("s_waitcnt vmcnt(" #n ")" ::: "memory")
; #define PG8_WAIT_L(n) asm volatile("s_waitcnt lgkmcnt(" #n ")" ::: "memory")
; #define PG8_BAR __builtin_amdgcn_s_barrier()
; #define PG8_SCHED __builtin_amdgcn_sched_barrier(0)
; template <class Epi, class Sched, class GemmT>
; __device__ __forceinline__ void gemm_phase(LAS unsigned char* lds, const GemmT& g, const Sched& S, const Epi& E, const int wid) {
;     ...
;                 PG8_LDB(B0, 1, 0); PG8_LDB(B1, 1, 1); PG8_SCHED; PG8_LDA(At, 1, 0); PG8_STAGE(PG8_SA(0, 1), a2 + hA2, vA2);
;                 PG8_WAIT_V(8); PG8_WAIT_L(0); PG8_BAR; PG8_MMA(0, 0, At, B0); PG8_MMA(0, 1, At, B1); PG8_BAR; PG8_SCHED;
;                 PG8_LDA(At, 1, 1); PG8_STAGE(PG8_SB(1, 0), b3, vB2); PG8_STAGE(PG8_SB(1, 1), b3 + hB2, vB2); PG8_STAGE(PG8_SA(1, 0), a3, vA2);
;                 PG8_WAIT_V(8); PG8_WAIT_L(0); PG8_BAR; PG8_MMA(1, 0, At, B0); PG8_MMA(1, 1, At, B1); PG8_BAR; PG8_SCHED;
;             }
	s_add_i32 s39, 0, 0x18000
	s_add_i32 s48, 0, 0x1c000
	v_add_u32_e32 v140, s39, v187
	v_add_u32_e32 v144, s39, v190
	v_add_u32_e32 v156, s48, v187
	v_add_u32_e32 v160, s48, v190
	ds_read_b128 v[140:143], v140
	ds_read_b128 v[144:147], v144
	ds_read_b128 v[148:151], v202
	ds_read_b128 v[152:155], v203
	ds_read_b128 v[156:159], v156
	ds_read_b128 v[160:163], v160
	ds_read_b128 v[164:167], v204
	ds_read_b128 v[168:171], v205
	s_add_u32 s40, s86, 0x100000
	s_addc_u32 s41, s87, 0
	s_mov_b32 m0, s93
	ds_read_b128 v[172:175], v200 offset:32768
	ds_read_b128 v[208:211], v200 offset:34816
	ds_read_b128 v[212:215], v201 offset:32768
	ds_read_b128 v[216:219], v201 offset:34816
	ds_read_b128 v[220:223], v200 offset:36864
	ds_read_b128 v[224:227], v200 offset:38912
	ds_read_b128 v[230:233], v201 offset:36864
	ds_read_b128 v[234:237], v201 offset:38912
	global_load_lds_dwordx4 v128, s[40:41]
	s_mov_b32 m0, s6
	s_nop 0
	global_load_lds_dwordx4 v132, s[40:41]
	s_waitcnt vmcnt(8)
	s_waitcnt lgkmcnt(0)
	s_waitcnt lgkmcnt(0)
	v_mfma_f32_16x16x32_bf16 v[124:127], v[140:143], v[172:175], v[124:127]
	v_mfma_f32_16x16x32_bf16 v[124:127], v[144:147], v[212:215], v[124:127]
	v_mfma_f32_16x16x32_bf16 v[120:123], v[152:155], v[212:215], v[120:123]
	v_mfma_f32_16x16x32_bf16 v[120:123], v[148:151], v[172:175], v[120:123]
	s_barrier
	s_setprio 3
	v_mfma_f32_16x16x32_bf16 v[112:115], v[148:151], v[208:211], v[112:115]
	v_mfma_f32_16x16x32_bf16 v[112:115], v[152:155], v[216:219], v[112:115]
	v_mfma_f32_16x16x32_bf16 v[116:119], v[144:147], v[216:219], v[116:119]
	v_mfma_f32_16x16x32_bf16 v[116:119], v[140:143], v[208:211], v[116:119]
	v_mfma_f32_16x16x32_bf16 v[100:103], v[140:143], v[220:223], v[100:103]
	v_mfma_f32_16x16x32_bf16 v[100:103], v[144:147], v[230:233], v[100:103]
	v_mfma_f32_16x16x32_bf16 v[96:99], v[152:155], v[230:233], v[96:99]
	v_mfma_f32_16x16x32_bf16 v[96:99], v[148:151], v[220:223], v[96:99]
	v_mfma_f32_16x16x32_bf16 v[76:79], v[148:151], v[224:227], v[76:79]
	v_mfma_f32_16x16x32_bf16 v[76:79], v[152:155], v[234:237], v[76:79]
	v_mfma_f32_16x16x32_bf16 v[84:87], v[144:147], v[234:237], v[84:87]
	v_mfma_f32_16x16x32_bf16 v[84:87], v[140:143], v[224:227], v[84:87]
	s_setprio 0
	s_setprio 3
	v_mfma_f32_16x16x32_bf16 v[108:111], v[156:159], v[172:175], v[108:111]
	v_mfma_f32_16x16x32_bf16 v[108:111], v[160:163], v[212:215], v[108:111]
	v_mfma_f32_16x16x32_bf16 v[104:107], v[168:171], v[212:215], v[104:107]
	v_mfma_f32_16x16x32_bf16 v[104:107], v[164:167], v[172:175], v[104:107]
	v_mfma_f32_16x16x32_bf16 v[88:91], v[164:167], v[208:211], v[88:91]
	v_mfma_f32_16x16x32_bf16 v[88:91], v[168:171], v[216:219], v[88:91]
	v_mfma_f32_16x16x32_bf16 v[92:95], v[160:163], v[216:219], v[92:95]
	v_mfma_f32_16x16x32_bf16 v[92:95], v[156:159], v[208:211], v[92:95]
	v_mfma_f32_16x16x32_bf16 v[68:71], v[156:159], v[220:223], v[68:71]
	v_mfma_f32_16x16x32_bf16 v[68:71], v[160:163], v[230:233], v[68:71]
	v_mfma_f32_16x16x32_bf16 v[64:67], v[168:171], v[230:233], v[64:67]
	v_mfma_f32_16x16x32_bf16 v[64:67], v[164:167], v[220:223], v[64:67]
	v_mfma_f32_16x16x32_bf16 v[40:43], v[164:167], v[224:227], v[40:43]
	v_mfma_f32_16x16x32_bf16 v[40:43], v[168:171], v[234:237], v[40:43]
	v_mfma_f32_16x16x32_bf16 v[48:51], v[160:163], v[234:237], v[48:51]
	v_mfma_f32_16x16x32_bf16 v[48:51], v[156:159], v[224:227], v[48:51]
	s_setprio 0
	s_barrier
	s_add_i32 s39, s39, s68
	s_mov_b32 m0, s39
	ds_read_b128 v[172:175], v200 offset:49152
	ds_read_b128 v[208:211], v200 offset:51200
	ds_read_b128 v[212:215], v201 offset:49152
	ds_read_b128 v[216:219], v201 offset:51200
	ds_read_b128 v[220:223], v200 offset:53248
	ds_read_b128 v[224:227], v200 offset:55296
	ds_read_b128 v[230:233], v201 offset:53248
	ds_read_b128 v[234:237], v201 offset:55296
	s_add_u32 s98, s70, 0x80
	s_addc_u32 s99, s71, 0
	s_nop 0
	global_load_lds_dwordx4 v130, s[98:99]
	s_add_i32 m0, s39, 0x2000
	s_add_u32 s40, s70, 0x100080
	s_addc_u32 s41, s71, 0
	s_add_i32 s39, s48, s68
	global_load_lds_dwordx4 v134, s[98:99]
	s_mov_b32 m0, s39
	s_nop 0
	global_load_lds_dwordx4 v130, s[40:41]
	s_add_i32 m0, s39, 0x2000
	s_nop 0
	global_load_lds_dwordx4 v134, s[40:41]
	s_mov_b32 m0, s7
	s_nop 0
	s_add_u32 s98, s86, 0x80
	s_addc_u32 s99, s87, 0
	s_nop 0
	global_load_lds_dwordx4 v128, s[98:99]
	s_mov_b32 m0, s12
	s_nop 0
	global_load_lds_dwordx4 v132, s[98:99]
	s_waitcnt vmcnt(8)
	s_waitcnt lgkmcnt(0)
	s_waitcnt lgkmcnt(0)
	v_mfma_f32_16x16x32_bf16 v[28:31], v[140:143], v[172:175], v[28:31]
	v_mfma_f32_16x16x32_bf16 v[28:31], v[144:147], v[212:215], v[28:31]
	v_mfma_f32_16x16x32_bf16 v[24:27], v[152:155], v[212:215], v[24:27]
	v_mfma_f32_16x16x32_bf16 v[24:27], v[148:151], v[172:175], v[24:27]
	s_barrier
	s_setprio 3
	v_mfma_f32_16x16x32_bf16 v[16:19], v[148:151], v[208:211], v[16:19]
	v_mfma_f32_16x16x32_bf16 v[16:19], v[152:155], v[216:219], v[16:19]
	v_mfma_f32_16x16x32_bf16 v[20:23], v[144:147], v[216:219], v[20:23]
	v_mfma_f32_16x16x32_bf16 v[20:23], v[140:143], v[208:211], v[20:23]
	v_mfma_f32_16x16x32_bf16 v[12:15], v[140:143], v[220:223], v[12:15]
	v_mfma_f32_16x16x32_bf16 v[12:15], v[144:147], v[230:233], v[12:15]
	v_mfma_f32_16x16x32_bf16 v[8:11], v[152:155], v[230:233], v[8:11]
	v_mfma_f32_16x16x32_bf16 v[8:11], v[148:151], v[220:223], v[8:11]
	v_mfma_f32_16x16x32_bf16 v[0:3], v[148:151], v[224:227], v[0:3]
	v_mfma_f32_16x16x32_bf16 v[0:3], v[152:155], v[234:237], v[0:3]
	v_mfma_f32_16x16x32_bf16 v[4:7], v[144:147], v[234:237], v[4:7]
	v_mfma_f32_16x16x32_bf16 v[4:7], v[140:143], v[224:227], v[4:7]
	s_setprio 0
	s_setprio 3
	v_mfma_f32_16x16x32_bf16 v[80:83], v[156:159], v[172:175], v[80:83]
	v_mfma_f32_16x16x32_bf16 v[80:83], v[160:163], v[212:215], v[80:83]
	v_mfma_f32_16x16x32_bf16 v[72:75], v[168:171], v[212:215], v[72:75]
	v_mfma_f32_16x16x32_bf16 v[72:75], v[164:167], v[172:175], v[72:75]
	v_mfma_f32_16x16x32_bf16 v[56:59], v[164:167], v[208:211], v[56:59]
	v_mfma_f32_16x16x32_bf16 v[56:59], v[168:171], v[216:219], v[56:59]
	v_mfma_f32_16x16x32_bf16 v[60:63], v[160:163], v[216:219], v[60:63]
	v_mfma_f32_16x16x32_bf16 v[60:63], v[156:159], v[208:211], v[60:63]
	v_mfma_f32_16x16x32_bf16 v[52:55], v[156:159], v[220:223], v[52:55]
	v_mfma_f32_16x16x32_bf16 v[52:55], v[160:163], v[230:233], v[52:55]
	v_mfma_f32_16x16x32_bf16 v[44:47], v[168:171], v[230:233], v[44:47]
	v_mfma_f32_16x16x32_bf16 v[44:47], v[164:167], v[220:223], v[44:47]
	v_mfma_f32_16x16x32_bf16 v[32:35], v[164:167], v[224:227], v[32:35]
	v_mfma_f32_16x16x32_bf16 v[32:35], v[168:171], v[234:237], v[32:35]
	v_mfma_f32_16x16x32_bf16 v[36:39], v[160:163], v[234:237], v[36:39]
	v_mfma_f32_16x16x32_bf16 v[36:39], v[156:159], v[224:227], v[36:39]
	s_setprio 0
	s_barrier
	s_add_i32 s38, s38, 2
	s_add_u32 s84, s84, 0x100
	s_addc_u32 s85, s85, 0
	s_add_u32 s36, s36, 0x100
	s_addc_u32 s37, s37, 0
	s_cmp_gt_u32 s38, 61
	s_cbranch_scc0 .LBB0_417
	s_and_b64 vcc, exec, s[20:21]
	s_cbranch_vccz .LBB0_420
	s_barrier

; #define PG8_STAGE(bufoff, gbase, voff) do { _Pragma("unroll") for (int _i = 0; _i < 2; ++_i) \
;         __builtin_amdgcn_global_load_lds((const unsigned*)((const char*)(gbase) + (voff)[_i]), (LAS unsigned*)(lds + (bufoff) + ldsw + _i * 8192), 16, 0, 0); } while (0)
; #define PG8_LDA(dst, b, h) do { _Pragma("unroll") for (int m = 0; m < 4; ++m) _Pragma("unroll") for (int k = 0; k < 2; ++k) dst[m][k] = *(const LAS bf16x8*)(lds + PG8_SA(b, h) + aoffk[k] + m * 2048); } while (0)
; #define PG8_LDB(dst, b, h) do { _Pragma("unroll") for (int n = 0; n < 2; ++n) _Pragma("unroll") for (int k = 0; k < 2; ++k) dst[n][k] = *(const LAS bf16x8*)(lds + PG8_SB(b, h) + boffk[k] + n * 2048); } while (0)
; #define PG8_WAIT_V(n) asm volatile("s_waitcnt vmcnt(" #n ")" ::: "memory")
; #define PG8_WAIT_L(n) asm volatile("s_waitcnt lgkmcnt(" #n ")" ::: "memory")
; #define PG8_BAR __builtin_amdgcn_s_barrier()
; #define PG8_SCHED __builtin_amdgcn_sched_barrier(0)
; template <class Epi, class Sched, class GemmT>
; __device__ __forceinline__ void gemm_phase(LAS unsigned char* lds, const GemmT& g, const Sched& S, const Epi& E, const int wid) {
;     ...
;                 PG8_LDB(B0, 0, 0); PG8_LDB(B1, 0, 1); PG8_SCHED; PG8_LDA(At, 0, 0); PG8_STAGE(PG8_SA(1, 1), a1 + hstepA, voffA);
;                 PG8_WAIT_V(8); PG8_WAIT_L(0); PG8_BAR; PG8_MMA(0, 0, At, B0); PG8_MMA(0, 1, At, B1); PG8_BAR; PG8_SCHED;
;                 PG8_LDA(At, 0, 1); PG8_STAGE(PG8_SB(0, 0), b2, vB2); PG8_STAGE(PG8_SB(0, 1), b2 + hB2, vB2); PG8_STAGE(PG8_SA(0, 0), a2, vA2);
;                 PG8_WAIT_V(8); PG8_WAIT_L(0); PG8_BAR; PG8_MMA(1, 0, At, B0); PG8_MMA(1, 1, At, B1); PG8_BAR; PG8_SCHED;
.LBB0_846:
	ds_read_b128 v[128:131], v194
	ds_read_b128 v[132:135], v195
	ds_read_b128 v[136:139], v196
	ds_read_b128 v[140:143], v197
	ds_read_b128 v[144:147], v198
	ds_read_b128 v[148:151], v199
	ds_read_b128 v[152:155], v200
	ds_read_b128 v[168:171], v201
	s_add_u32 s44, s42, 0xfff00080
	s_addc_u32 s45, s43, -1
	s_cmp_eq_u32 s62, 60
	s_cselect_b32 s51, s37, s45
	s_cselect_b32 s50, s36, s44
	s_cselect_b32 s45, s59, s61
	s_cselect_b32 s44, s41, s60
	s_add_i32 m0, s14, 0xc000
	ds_read_b128 v[172:175], v202
	ds_read_b128 v[176:179], v202 offset:2048
	ds_read_b128 v[180:183], v203
	ds_read_b128 v[184:187], v203 offset:2048
	ds_read_b128 v[208:211], v202 offset:4096
	ds_read_b128 v[212:215], v202 offset:6144
	ds_read_b128 v[216:219], v203 offset:4096
	ds_read_b128 v[220:223], v203 offset:6144
	global_load_lds_dwordx4 v156, s[42:43]
	s_add_i32 m0, s14, 0xe000
	s_nop 0
	global_load_lds_dwordx4 v160, s[42:43]
	s_waitcnt vmcnt(8)
	s_waitcnt lgkmcnt(0)
	s_waitcnt lgkmcnt(0)
	v_mfma_f32_16x16x32_bf16 v[124:127], v[128:131], v[172:175], v[124:127]
	v_mfma_f32_16x16x32_bf16 v[124:127], v[132:135], v[180:183], v[124:127]
	v_mfma_f32_16x16x32_bf16 v[120:123], v[140:143], v[180:183], v[120:123]
	v_mfma_f32_16x16x32_bf16 v[120:123], v[136:139], v[172:175], v[120:123]
	s_barrier
	s_setprio 3
	v_mfma_f32_16x16x32_bf16 v[104:107], v[136:139], v[176:179], v[104:107]
	v_mfma_f32_16x16x32_bf16 v[104:107], v[140:143], v[184:187], v[104:107]
	v_mfma_f32_16x16x32_bf16 v[108:111], v[132:135], v[184:187], v[108:111]
	v_mfma_f32_16x16x32_bf16 v[108:111], v[128:131], v[176:179], v[108:111]
	v_mfma_f32_16x16x32_bf16 v[92:95], v[128:131], v[208:211], v[92:95]
	v_mfma_f32_16x16x32_bf16 v[92:95], v[132:135], v[216:219], v[92:95]
	v_mfma_f32_16x16x32_bf16 v[88:91], v[140:143], v[216:219], v[88:91]
	v_mfma_f32_16x16x32_bf16 v[88:91], v[136:139], v[208:211], v[88:91]
	v_mfma_f32_16x16x32_bf16 v[72:75], v[136:139], v[212:215], v[72:75]
	v_mfma_f32_16x16x32_bf16 v[72:75], v[140:143], v[220:223], v[72:75]
	v_mfma_f32_16x16x32_bf16 v[76:79], v[132:135], v[220:223], v[76:79]
	v_mfma_f32_16x16x32_bf16 v[76:79], v[128:131], v[212:215], v[76:79]
	s_setprio 0
	s_setprio 3
	v_mfma_f32_16x16x32_bf16 v[116:119], v[144:147], v[172:175], v[116:119]
	v_mfma_f32_16x16x32_bf16 v[116:119], v[148:151], v[180:183], v[116:119]
	v_mfma_f32_16x16x32_bf16 v[112:115], v[168:171], v[180:183], v[112:115]
	v_mfma_f32_16x16x32_bf16 v[112:115], v[152:155], v[172:175], v[112:115]
	v_mfma_f32_16x16x32_bf16 v[96:99], v[152:155], v[176:179], v[96:99]
	v_mfma_f32_16x16x32_bf16 v[96:99], v[168:171], v[184:187], v[96:99]
	v_mfma_f32_16x16x32_bf16 v[100:103], v[148:151], v[184:187], v[100:103]
	v_mfma_f32_16x16x32_bf16 v[100:103], v[144:147], v[176:179], v[100:103]
	v_mfma_f32_16x16x32_bf16 v[84:87], v[144:147], v[208:211], v[84:87]
	v_mfma_f32_16x16x32_bf16 v[84:87], v[148:151], v[216:219], v[84:87]
	v_mfma_f32_16x16x32_bf16 v[80:83], v[168:171], v[216:219], v[80:83]
	v_mfma_f32_16x16x32_bf16 v[80:83], v[152:155], v[208:211], v[80:83]
	v_mfma_f32_16x16x32_bf16 v[64:67], v[152:155], v[212:215], v[64:67]
	v_mfma_f32_16x16x32_bf16 v[64:67], v[168:171], v[220:223], v[64:67]
	v_mfma_f32_16x16x32_bf16 v[68:71], v[148:151], v[220:223], v[68:71]
	v_mfma_f32_16x16x32_bf16 v[68:71], v[144:147], v[212:215], v[68:71]
	s_setprio 0
	s_barrier
	s_add_i32 s48, s54, s68
	s_mov_b32 m0, s48
	ds_read_b128 v[172:175], v202 offset:16384
	ds_read_b128 v[176:179], v202 offset:18432
	ds_read_b128 v[180:183], v203 offset:16384
	ds_read_b128 v[184:187], v203 offset:18432
	ds_read_b128 v[208:211], v202 offset:20480
	ds_read_b128 v[212:215], v202 offset:22528
	ds_read_b128 v[216:219], v203 offset:20480
	ds_read_b128 v[220:223], v203 offset:22528
	global_load_lds_dwordx4 v158, s[44:45]
	s_add_i32 m0, s48, 0x2000
	s_add_u32 s48, s44, 0x100000
	s_addc_u32 s49, s45, 0
	s_add_i32 s63, s55, s68
	global_load_lds_dwordx4 v162, s[44:45]
	s_mov_b32 m0, s63
	s_nop 0
	global_load_lds_dwordx4 v158, s[48:49]
	s_add_i32 m0, s63, 0x2000
	s_nop 0
	global_load_lds_dwordx4 v162, s[48:49]
	s_mov_b32 m0, s14
	s_nop 0
	global_load_lds_dwordx4 v156, s[50:51]
	s_mov_b32 m0, s15
	s_nop 0
	global_load_lds_dwordx4 v160, s[50:51]
	s_waitcnt vmcnt(8)
	s_waitcnt lgkmcnt(0)
	s_waitcnt lgkmcnt(0)
	v_mfma_f32_16x16x32_bf16 v[52:55], v[128:131], v[172:175], v[52:55]
	v_mfma_f32_16x16x32_bf16 v[52:55], v[132:135], v[180:183], v[52:55]
	v_mfma_f32_16x16x32_bf16 v[48:51], v[140:143], v[180:183], v[48:51]
	v_mfma_f32_16x16x32_bf16 v[48:51], v[136:139], v[172:175], v[48:51]
	s_barrier
	s_setprio 3
	v_mfma_f32_16x16x32_bf16 v[32:35], v[136:139], v[176:179], v[32:35]
	v_mfma_f32_16x16x32_bf16 v[32:35], v[140:143], v[184:187], v[32:35]
	v_mfma_f32_16x16x32_bf16 v[36:39], v[132:135], v[184:187], v[36:39]
	v_mfma_f32_16x16x32_bf16 v[36:39], v[128:131], v[176:179], v[36:39]
	v_mfma_f32_16x16x32_bf16 v[20:23], v[128:131], v[208:211], v[20:23]
	v_mfma_f32_16x16x32_bf16 v[20:23], v[132:135], v[216:219], v[20:23]
	v_mfma_f32_16x16x32_bf16 v[16:19], v[140:143], v[216:219], v[16:19]
	v_mfma_f32_16x16x32_bf16 v[16:19], v[136:139], v[208:211], v[16:19]
	v_mfma_f32_16x16x32_bf16 v[0:3], v[136:139], v[212:215], v[0:3]
	v_mfma_f32_16x16x32_bf16 v[0:3], v[140:143], v[220:223], v[0:3]
	v_mfma_f32_16x16x32_bf16 v[4:7], v[132:135], v[220:223], v[4:7]
	v_mfma_f32_16x16x32_bf16 v[4:7], v[128:131], v[212:215], v[4:7]
	s_setprio 0
	s_setprio 3
	v_mfma_f32_16x16x32_bf16 v[60:63], v[144:147], v[172:175], v[60:63]
	v_mfma_f32_16x16x32_bf16 v[60:63], v[148:151], v[180:183], v[60:63]
	v_mfma_f32_16x16x32_bf16 v[56:59], v[168:171], v[180:183], v[56:59]
	v_mfma_f32_16x16x32_bf16 v[56:59], v[152:155], v[172:175], v[56:59]
	v_mfma_f32_16x16x32_bf16 v[40:43], v[152:155], v[176:179], v[40:43]
	v_mfma_f32_16x16x32_bf16 v[40:43], v[168:171], v[184:187], v[40:43]
	v_mfma_f32_16x16x32_bf16 v[44:47], v[148:151], v[184:187], v[44:47]
	v_mfma_f32_16x16x32_bf16 v[44:47], v[144:147], v[176:179], v[44:47]
	v_mfma_f32_16x16x32_bf16 v[28:31], v[144:147], v[208:211], v[28:31]
	v_mfma_f32_16x16x32_bf16 v[28:31], v[148:151], v[216:219], v[28:31]
	v_mfma_f32_16x16x32_bf16 v[24:27], v[168:171], v[216:219], v[24:27]
	v_mfma_f32_16x16x32_bf16 v[24:27], v[152:155], v[208:211], v[24:27]
	v_mfma_f32_16x16x32_bf16 v[8:11], v[152:155], v[212:215], v[8:11]
	v_mfma_f32_16x16x32_bf16 v[8:11], v[168:171], v[220:223], v[8:11]
	v_mfma_f32_16x16x32_bf16 v[12:15], v[148:151], v[220:223], v[12:15]
	v_mfma_f32_16x16x32_bf16 v[12:15], v[144:147], v[212:215], v[12:15]
	s_setprio 0
	s_barrier
; #define PG8_STAGE(bufoff, gbase, voff) do { _Pragma("unroll") for (int _i = 0; _i < 2; ++_i) \
;         __builtin_amdgcn_global_load_lds((const unsigned*)((const char*)(gbase) + (voff)[_i]), (LAS unsigned*)(lds + (bufoff) + ldsw + _i * 8192), 16, 0, 0); } while (0)
; #define PG8_LDA(dst, b, h) do { _Pragma("unroll") for (int m = 0; m < 4; ++m) _Pragma("unroll") for (int k = 0; k < 2; ++k) dst[m][k] = *(const LAS bf16x8*)(lds + PG8_SA(b, h) + aoffk[k] + m * 2048); } while (0)
; #define PG8_LDB(dst, b, h) do { _Pragma("unroll") for (int n = 0; n < 2; ++n) _Pragma("unroll") for (int k = 0; k < 2; ++k) dst[n][k] = *(const LAS bf16x8*)(lds + PG8_SB(b, h) + boffk[k] + n * 2048); } while (0)
; #define PG8_WAIT_V(n) asm volatile("s_waitcnt vmcnt(" #n ")" ::: "memory")
; #define PG8_WAIT_L(n) asm volatile("s_waitcnt lgkmcnt(" #n ")" ::: "memory")
; #define PG8_BAR __builtin_amdgcn_s_barrier()
; #define PG8_SCHED __builtin_amdgcn_sched_barrier(0)
; template <class Epi, class Sched, class GemmT>
; __device__ __forceinline__ void gemm_phase(LAS unsigned char* lds, const GemmT& g, const Sched& S, const Epi& E, const int wid) {
;     ...
;                 PG8_LDB(B0, 1, 0); PG8_LDB(B1, 1, 1); PG8_SCHED; PG8_LDA(At, 1, 0); PG8_STAGE(PG8_SA(0, 1), a2 + hA2, vA2);
;                 PG8_WAIT_V(8); PG8_WAIT_L(0); PG8_BAR; PG8_MMA(0, 0, At, B0); PG8_MMA(0, 1, At, B1); PG8_BAR; PG8_SCHED;
;                 PG8_LDA(At, 1, 1); PG8_STAGE(PG8_SB(1, 0), b3, vB2); PG8_STAGE(PG8_SB(1, 1), b3 + hB2, vB2); PG8_STAGE(PG8_SA(1, 0), a3, vA2);
;                 PG8_WAIT_V(8); PG8_WAIT_L(0); PG8_BAR; PG8_MMA(1, 0, At, B0); PG8_MMA(1, 1, At, B1); PG8_BAR; PG8_SCHED;
;             }
	s_add_i32 s63, 0, 0x18000
	s_add_i32 s64, 0, 0x1c000
	v_add_u32_e32 v128, s63, v191
	v_add_u32_e32 v132, s63, v192
	v_add_u32_e32 v144, s64, v191
	v_add_u32_e32 v148, s64, v192
	ds_read_b128 v[128:131], v128
	ds_read_b128 v[132:135], v132
	ds_read_b128 v[136:139], v204
	ds_read_b128 v[140:143], v205
	ds_read_b128 v[144:147], v144
	ds_read_b128 v[148:151], v148
	ds_read_b128 v[152:155], v206
	ds_read_b128 v[168:171], v207
	s_add_u32 s48, s50, 0x100000
	s_addc_u32 s49, s51, 0
	s_mov_b32 m0, s22
	ds_read_b128 v[172:175], v202 offset:32768
	ds_read_b128 v[176:179], v202 offset:34816
	ds_read_b128 v[180:183], v203 offset:32768
	ds_read_b128 v[184:187], v203 offset:34816
	ds_read_b128 v[208:211], v202 offset:36864
	ds_read_b128 v[212:215], v202 offset:38912
	ds_read_b128 v[216:219], v203 offset:36864
	ds_read_b128 v[220:223], v203 offset:38912
	global_load_lds_dwordx4 v156, s[48:49]
	s_mov_b32 m0, s23
	s_nop 0
	global_load_lds_dwordx4 v160, s[48:49]
	s_waitcnt vmcnt(8)
	s_waitcnt lgkmcnt(0)
	s_waitcnt lgkmcnt(0)
	v_mfma_f32_16x16x32_bf16 v[124:127], v[128:131], v[172:175], v[124:127]
	v_mfma_f32_16x16x32_bf16 v[124:127], v[132:135], v[180:183], v[124:127]
	v_mfma_f32_16x16x32_bf16 v[120:123], v[140:143], v[180:183], v[120:123]
	v_mfma_f32_16x16x32_bf16 v[120:123], v[136:139], v[172:175], v[120:123]
	s_barrier
	s_setprio 3
	v_mfma_f32_16x16x32_bf16 v[104:107], v[136:139], v[176:179], v[104:107]
	v_mfma_f32_16x16x32_bf16 v[104:107], v[140:143], v[184:187], v[104:107]
	v_mfma_f32_16x16x32_bf16 v[108:111], v[132:135], v[184:187], v[108:111]
	v_mfma_f32_16x16x32_bf16 v[108:111], v[128:131], v[176:179], v[108:111]
	v_mfma_f32_16x16x32_bf16 v[92:95], v[128:131], v[208:211], v[92:95]
	v_mfma_f32_16x16x32_bf16 v[92:95], v[132:135], v[216:219], v[92:95]
	v_mfma_f32_16x16x32_bf16 v[88:91], v[140:143], v[216:219], v[88:91]
	v_mfma_f32_16x16x32_bf16 v[88:91], v[136:139], v[208:211], v[88:91]
	v_mfma_f32_16x16x32_bf16 v[72:75], v[136:139], v[212:215], v[72:75]
	v_mfma_f32_16x16x32_bf16 v[72:75], v[140:143], v[220:223], v[72:75]
	v_mfma_f32_16x16x32_bf16 v[76:79], v[132:135], v[220:223], v[76:79]
	v_mfma_f32_16x16x32_bf16 v[76:79], v[128:131], v[212:215], v[76:79]
	s_setprio 0
	s_setprio 3
	v_mfma_f32_16x16x32_bf16 v[116:119], v[144:147], v[172:175], v[116:119]
	v_mfma_f32_16x16x32_bf16 v[116:119], v[148:151], v[180:183], v[116:119]
	v_mfma_f32_16x16x32_bf16 v[112:115], v[168:171], v[180:183], v[112:115]
	v_mfma_f32_16x16x32_bf16 v[112:115], v[152:155], v[172:175], v[112:115]
	v_mfma_f32_16x16x32_bf16 v[96:99], v[152:155], v[176:179], v[96:99]
	v_mfma_f32_16x16x32_bf16 v[96:99], v[168:171], v[184:187], v[96:99]
	v_mfma_f32_16x16x32_bf16 v[100:103], v[148:151], v[184:187], v[100:103]
	v_mfma_f32_16x16x32_bf16 v[100:103], v[144:147], v[176:179], v[100:103]
	v_mfma_f32_16x16x32_bf16 v[84:87], v[144:147], v[208:211], v[84:87]
	v_mfma_f32_16x16x32_bf16 v[84:87], v[148:151], v[216:219], v[84:87]
	v_mfma_f32_16x16x32_bf16 v[80:83], v[168:171], v[216:219], v[80:83]
	v_mfma_f32_16x16x32_bf16 v[80:83], v[152:155], v[208:211], v[80:83]
	v_mfma_f32_16x16x32_bf16 v[64:67], v[152:155], v[212:215], v[64:67]
	v_mfma_f32_16x16x32_bf16 v[64:67], v[168:171], v[220:223], v[64:67]
	v_mfma_f32_16x16x32_bf16 v[68:71], v[148:151], v[220:223], v[68:71]
	v_mfma_f32_16x16x32_bf16 v[68:71], v[144:147], v[212:215], v[68:71]
	s_setprio 0
	s_barrier
	s_add_i32 s48, s63, s68
	s_mov_b32 m0, s48
	ds_read_b128 v[172:175], v202 offset:49152
	ds_read_b128 v[176:179], v202 offset:51200
	ds_read_b128 v[180:183], v203 offset:49152
	ds_read_b128 v[184:187], v203 offset:51200
	ds_read_b128 v[208:211], v202 offset:53248
	ds_read_b128 v[212:215], v202 offset:55296
	ds_read_b128 v[216:219], v203 offset:53248
	ds_read_b128 v[220:223], v203 offset:55296
	s_add_u32 s98, s44, 0x80
	s_addc_u32 s99, s45, 0
	s_nop 0
	global_load_lds_dwordx4 v158, s[98:99]
	s_add_i32 m0, s48, 0x2000
	s_add_u32 s44, s44, 0x100080
	s_addc_u32 s45, s45, 0
	s_add_i32 s48, s64, s68
	global_load_lds_dwordx4 v162, s[98:99]
	s_mov_b32 m0, s48
	s_nop 0
	global_load_lds_dwordx4 v158, s[44:45]
	s_add_i32 m0, s48, 0x2000
	s_nop 0
	global_load_lds_dwordx4 v162, s[44:45]
	s_mov_b32 m0, s34
	s_nop 0
	s_add_u32 s98, s50, 0x80
	s_addc_u32 s99, s51, 0
	s_nop 0
	global_load_lds_dwordx4 v156, s[98:99]
	s_mov_b32 m0, s35
	s_nop 0
	global_load_lds_dwordx4 v160, s[98:99]
	s_waitcnt vmcnt(8)
	s_waitcnt lgkmcnt(0)
	s_waitcnt lgkmcnt(0)
	v_mfma_f32_16x16x32_bf16 v[52:55], v[128:131], v[172:175], v[52:55]
	v_mfma_f32_16x16x32_bf16 v[52:55], v[132:135], v[180:183], v[52:55]
	v_mfma_f32_16x16x32_bf16 v[48:51], v[140:143], v[180:183], v[48:51]
	v_mfma_f32_16x16x32_bf16 v[48:51], v[136:139], v[172:175], v[48:51]
	s_barrier
	s_setprio 3
	v_mfma_f32_16x16x32_bf16 v[32:35], v[136:139], v[176:179], v[32:35]
	v_mfma_f32_16x16x32_bf16 v[32:35], v[140:143], v[184:187], v[32:35]
	v_mfma_f32_16x16x32_bf16 v[36:39], v[132:135], v[184:187], v[36:39]
	v_mfma_f32_16x16x32_bf16 v[36:39], v[128:131], v[176:179], v[36:39]
	v_mfma_f32_16x16x32_bf16 v[20:23], v[128:131], v[208:211], v[20:23]
	v_mfma_f32_16x16x32_bf16 v[20:23], v[132:135], v[216:219], v[20:23]
	v_mfma_f32_16x16x32_bf16 v[16:19], v[140:143], v[216:219], v[16:19]
	v_mfma_f32_16x16x32_bf16 v[16:19], v[136:139], v[208:211], v[16:19]
	v_mfma_f32_16x16x32_bf16 v[0:3], v[136:139], v[212:215], v[0:3]
	v_mfma_f32_16x16x32_bf16 v[0:3], v[140:143], v[220:223], v[0:3]
	v_mfma_f32_16x16x32_bf16 v[4:7], v[132:135], v[220:223], v[4:7]
	v_mfma_f32_16x16x32_bf16 v[4:7], v[128:131], v[212:215], v[4:7]
	s_setprio 0
	s_setprio 3
	v_mfma_f32_16x16x32_bf16 v[60:63], v[144:147], v[172:175], v[60:63]
	v_mfma_f32_16x16x32_bf16 v[60:63], v[148:151], v[180:183], v[60:63]
	v_mfma_f32_16x16x32_bf16 v[56:59], v[168:171], v[180:183], v[56:59]
	v_mfma_f32_16x16x32_bf16 v[56:59], v[152:155], v[172:175], v[56:59]
	v_mfma_f32_16x16x32_bf16 v[40:43], v[152:155], v[176:179], v[40:43]
	v_mfma_f32_16x16x32_bf16 v[40:43], v[168:171], v[184:187], v[40:43]
	v_mfma_f32_16x16x32_bf16 v[44:47], v[148:151], v[184:187], v[44:47]
	v_mfma_f32_16x16x32_bf16 v[44:47], v[144:147], v[176:179], v[44:47]
	v_mfma_f32_16x16x32_bf16 v[28:31], v[144:147], v[208:211], v[28:31]
	v_mfma_f32_16x16x32_bf16 v[28:31], v[148:151], v[216:219], v[28:31]
	v_mfma_f32_16x16x32_bf16 v[24:27], v[168:171], v[216:219], v[24:27]
	v_mfma_f32_16x16x32_bf16 v[24:27], v[152:155], v[208:211], v[24:27]
	v_mfma_f32_16x16x32_bf16 v[8:11], v[152:155], v[212:215], v[8:11]
	v_mfma_f32_16x16x32_bf16 v[8:11], v[168:171], v[220:223], v[8:11]
	v_mfma_f32_16x16x32_bf16 v[12:15], v[148:151], v[220:223], v[12:15]
	v_mfma_f32_16x16x32_bf16 v[12:15], v[144:147], v[212:215], v[12:15]
	s_setprio 0
	s_barrier
	s_add_i32 s62, s62, 2
	s_add_u32 s42, s42, 0x100
	s_addc_u32 s43, s43, 0
	s_add_u32 s60, s60, 0x100
	s_addc_u32 s61, s61, 0
	s_cmp_gt_u32 s62, 61
	s_cbranch_scc0 .LBB0_846
	s_and_b64 vcc, exec, s[20:21]
	s_cbranch_vccz .LBB0_849
	s_barrier

; #define PG8_STAGE(bufoff, gbase, voff) do { _Pragma("unroll") for (int _i = 0; _i < 2; ++_i) \
;         __builtin_amdgcn_global_load_lds((const unsigned*)((const char*)(gbase) + (voff)[_i]), (LAS unsigned*)(lds + (bufoff) + ldsw + _i * 8192), 16, 0, 0); } while (0)
; #define PG8_LDA(dst, b, h) do { _Pragma("unroll") for (int m = 0; m < 4; ++m) _Pragma("unroll") for (int k = 0; k < 2; ++k) dst[m][k] = *(const LAS bf16x8*)(lds + PG8_SA(b, h) + aoffk[k] + m * 2048); } while (0)
; #define PG8_LDB(dst, b, h) do { _Pragma("unroll") for (int n = 0; n < 2; ++n) _Pragma("unroll") for (int k = 0; k < 2; ++k) dst[n][k] = *(const LAS bf16x8*)(lds + PG8_SB(b, h) + boffk[k] + n * 2048); } while (0)
; #define PG8_WAIT_V(n) asm volatile("s_waitcnt vmcnt(" #n ")" ::: "memory")
; #define PG8_WAIT_L(n) asm volatile("s_waitcnt lgkmcnt(" #n ")" ::: "memory")
; #define PG8_BAR __builtin_amdgcn_s_barrier()
; #define PG8_SCHED __builtin_amdgcn_sched_barrier(0)
; template <class Epi, class Sched, class GemmT>
; __device__ __forceinline__ void gemm_phase(LAS unsigned char* lds, const GemmT& g, const Sched& S, const Epi& E, const int wid) {
;     ...
;                 PG8_LDB(B0, 0, 0); PG8_LDB(B1, 0, 1); PG8_SCHED; PG8_LDA(At, 0, 0); PG8_STAGE(PG8_SA(1, 1), a1 + hstepA, voffA);
;                 PG8_WAIT_V(8); PG8_WAIT_L(0); PG8_BAR; PG8_MMA(0, 0, At, B0); PG8_MMA(0, 1, At, B1); PG8_BAR; PG8_SCHED;
;                 PG8_LDA(At, 0, 1); PG8_STAGE(PG8_SB(0, 0), b2, vB2); PG8_STAGE(PG8_SB(0, 1), b2 + hB2, vB2); PG8_STAGE(PG8_SA(0, 0), a2, vA2);
;                 PG8_WAIT_V(8); PG8_WAIT_L(0); PG8_BAR; PG8_MMA(1, 0, At, B0); PG8_MMA(1, 1, At, B1); PG8_BAR; PG8_SCHED;
.LBB0_936:
	ds_read_b128 v[12:15], v223
	ds_read_b128 v[132:135], v224
	ds_read_b128 v[136:139], v225
	ds_read_b128 v[140:143], v226
	ds_read_b128 v[144:147], v227
	ds_read_b128 v[148:151], v229
	ds_read_b128 v[152:155], v230
	ds_read_b128 v[156:159], v231
	s_add_u32 s66, s64, 0xfff00080
	s_addc_u32 s67, s65, -1
	s_cmp_eq_u32 s81, 60
	s_cselect_b32 s71, s57, s67
	s_cselect_b32 s70, s56, s66
	s_cselect_b32 s67, s77, s79
	s_cselect_b32 s66, s63, s78
	s_add_i32 m0, s14, 0xc000
	ds_read_b128 v[160:163], v232
	ds_read_b128 v[164:167], v232 offset:2048
	ds_read_b128 v[168:171], v233
	ds_read_b128 v[172:175], v233 offset:2048
	ds_read_b128 v[188:191], v232 offset:4096
	ds_read_b128 v[192:195], v232 offset:6144
	ds_read_b128 v[196:199], v233 offset:4096
	ds_read_b128 v[200:203], v233 offset:6144
	global_load_lds_dwordx4 v176, s[64:65]
	s_add_i32 m0, s14, 0xe000
	s_nop 0
	global_load_lds_dwordx4 v180, s[64:65]
	s_waitcnt vmcnt(8)
	s_waitcnt lgkmcnt(0)
	s_waitcnt lgkmcnt(0)
	v_mfma_f32_16x16x32_bf16 v[124:127], v[12:15], v[160:163], v[124:127]
	v_mfma_f32_16x16x32_bf16 v[124:127], v[132:135], v[168:171], v[124:127]
	v_mfma_f32_16x16x32_bf16 v[120:123], v[140:143], v[168:171], v[120:123]
	v_mfma_f32_16x16x32_bf16 v[120:123], v[136:139], v[160:163], v[120:123]
	s_barrier
	s_setprio 3
	v_mfma_f32_16x16x32_bf16 v[104:107], v[136:139], v[164:167], v[104:107]
	v_mfma_f32_16x16x32_bf16 v[104:107], v[140:143], v[172:175], v[104:107]
	v_mfma_f32_16x16x32_bf16 v[40:43], v[132:135], v[172:175], v[40:43]
	v_mfma_f32_16x16x32_bf16 v[40:43], v[12:15], v[164:167], v[40:43]
	v_mfma_f32_16x16x32_bf16 v[32:35], v[12:15], v[188:191], v[32:35]
	v_mfma_f32_16x16x32_bf16 v[32:35], v[132:135], v[196:199], v[32:35]
	v_mfma_f32_16x16x32_bf16 v[96:99], v[140:143], v[196:199], v[96:99]
	v_mfma_f32_16x16x32_bf16 v[96:99], v[136:139], v[188:191], v[96:99]
	v_mfma_f32_16x16x32_bf16 v[92:95], v[136:139], v[192:195], v[92:95]
	v_mfma_f32_16x16x32_bf16 v[92:95], v[140:143], v[200:203], v[92:95]
	v_mfma_f32_16x16x32_bf16 v[112:115], v[132:135], v[200:203], v[112:115]
	v_mfma_f32_16x16x32_bf16 v[112:115], v[12:15], v[192:195], v[112:115]
	s_setprio 0
	s_setprio 3
	v_mfma_f32_16x16x32_bf16 v[68:71], v[144:147], v[160:163], v[68:71]
	v_mfma_f32_16x16x32_bf16 v[68:71], v[148:151], v[168:171], v[68:71]
	v_mfma_f32_16x16x32_bf16 v[60:63], v[156:159], v[168:171], v[60:63]
	v_mfma_f32_16x16x32_bf16 v[60:63], v[152:155], v[160:163], v[60:63]
	v_mfma_f32_16x16x32_bf16 v[20:23], v[152:155], v[164:167], v[20:23]
	v_mfma_f32_16x16x32_bf16 v[20:23], v[156:159], v[172:175], v[20:23]
	v_mfma_f32_16x16x32_bf16 v[76:79], v[148:151], v[172:175], v[76:79]
	v_mfma_f32_16x16x32_bf16 v[76:79], v[144:147], v[164:167], v[76:79]
	v_mfma_f32_16x16x32_bf16 v[72:75], v[144:147], v[188:191], v[72:75]
	v_mfma_f32_16x16x32_bf16 v[72:75], v[148:151], v[196:199], v[72:75]
	v_mfma_f32_16x16x32_bf16 v[16:19], v[156:159], v[196:199], v[16:19]
	v_mfma_f32_16x16x32_bf16 v[16:19], v[152:155], v[188:191], v[16:19]
	v_mfma_f32_16x16x32_bf16 v[80:83], v[152:155], v[192:195], v[80:83]
	v_mfma_f32_16x16x32_bf16 v[80:83], v[156:159], v[200:203], v[80:83]
	v_mfma_f32_16x16x32_bf16 v[84:87], v[148:151], v[200:203], v[84:87]
	v_mfma_f32_16x16x32_bf16 v[84:87], v[144:147], v[192:195], v[84:87]
	s_setprio 0
	s_barrier
	s_add_i32 s80, s69, s68
	s_mov_b32 m0, s80
	ds_read_b128 v[160:163], v232 offset:16384
	ds_read_b128 v[164:167], v232 offset:18432
	ds_read_b128 v[168:171], v233 offset:16384
	ds_read_b128 v[172:175], v233 offset:18432
	ds_read_b128 v[188:191], v232 offset:20480
	ds_read_b128 v[192:195], v232 offset:22528
	ds_read_b128 v[196:199], v233 offset:20480
	ds_read_b128 v[200:203], v233 offset:22528
	global_load_lds_dwordx4 v178, s[66:67]
	s_add_i32 m0, s80, 0x2000
	s_add_u32 s82, s66, 0x100000
	s_addc_u32 s83, s67, 0
	s_add_i32 s80, s72, s68
	global_load_lds_dwordx4 v182, s[66:67]
	s_mov_b32 m0, s80
	s_nop 0
	global_load_lds_dwordx4 v178, s[82:83]
	s_add_i32 m0, s80, 0x2000
	s_nop 0
	global_load_lds_dwordx4 v182, s[82:83]
	s_mov_b32 m0, s14
	s_nop 0
	s_add_u32 s100, s70, 0x80
	s_addc_u32 s101, s71, 0
	global_load_lds_dwordx4 v176, s[70:71]
	s_mov_b32 m0, s15
	s_nop 0
	global_load_lds_dwordx4 v180, s[70:71]
	s_waitcnt vmcnt(8)
	s_waitcnt lgkmcnt(0)
	s_waitcnt lgkmcnt(0)
	v_mfma_f32_16x16x32_bf16 v[56:59], v[12:15], v[160:163], v[56:59]
	v_mfma_f32_16x16x32_bf16 v[56:59], v[132:135], v[168:171], v[56:59]
	v_mfma_f32_16x16x32_bf16 v[108:111], v[136:139], v[160:163], v[108:111]
	v_mfma_f32_16x16x32_bf16 v[108:111], v[140:143], v[168:171], v[108:111]
	s_barrier
	s_setprio 3
	v_mfma_f32_16x16x32_bf16 v[36:39], v[12:15], v[164:167], v[36:39]
	v_mfma_f32_16x16x32_bf16 v[36:39], v[132:135], v[172:175], v[36:39]
	v_mfma_f32_16x16x32_bf16 v[100:103], v[136:139], v[164:167], v[100:103]
	v_mfma_f32_16x16x32_bf16 v[100:103], v[140:143], v[172:175], v[100:103]
	v_mfma_f32_16x16x32_bf16 v[28:31], v[12:15], v[188:191], v[28:31]
	v_mfma_f32_16x16x32_bf16 v[28:31], v[132:135], v[196:199], v[28:31]
	v_mfma_f32_16x16x32_bf16 v[88:91], v[136:139], v[188:191], v[88:91]
	v_mfma_f32_16x16x32_bf16 v[88:91], v[140:143], v[196:199], v[88:91]
	v_mfma_f32_16x16x32_bf16 v[24:27], v[136:139], v[192:195], v[24:27]
	v_mfma_f32_16x16x32_bf16 v[24:27], v[140:143], v[200:203], v[24:27]
	v_mfma_f32_16x16x32_bf16 v[12:15], v[12:15], v[192:195], v[64:67]
	v_mfma_f32_16x16x32_bf16 v[12:15], v[132:135], v[200:203], v[12:15]
	s_setprio 0
	s_setprio 3
	v_mfma_f32_16x16x32_bf16 v[64:67], v[144:147], v[192:195], v[116:119]
	v_mfma_f32_16x16x32_bf16 v[116:119], v[148:151], v[200:203], v[64:67]
	v_mfma_f32_16x16x32_bf16 v[44:47], v[144:147], v[160:163], v[44:47]
	v_mfma_f32_16x16x32_bf16 v[44:47], v[148:151], v[168:171], v[44:47]
	v_mfma_f32_16x16x32_bf16 v[0:3], v[152:155], v[160:163], v[0:3]
	v_mfma_f32_16x16x32_bf16 v[0:3], v[156:159], v[168:171], v[0:3]
	v_mfma_f32_16x16x32_bf16 v[48:51], v[144:147], v[164:167], v[48:51]
	v_mfma_f32_16x16x32_bf16 v[48:51], v[148:151], v[172:175], v[48:51]
	v_mfma_f32_16x16x32_bf16 v[4:7], v[152:155], v[164:167], v[4:7]
	v_mfma_f32_16x16x32_bf16 v[4:7], v[156:159], v[172:175], v[4:7]
	v_mfma_f32_16x16x32_bf16 v[64:67], v[152:155], v[192:195], v[128:131]
	v_mfma_f32_16x16x32_bf16 v[128:131], v[156:159], v[200:203], v[64:67]
	v_mfma_f32_16x16x32_bf16 v[52:55], v[144:147], v[188:191], v[52:55]
	v_mfma_f32_16x16x32_bf16 v[52:55], v[148:151], v[196:199], v[52:55]
	v_mfma_f32_16x16x32_bf16 v[8:11], v[152:155], v[188:191], v[8:11]
	v_mfma_f32_16x16x32_bf16 v[8:11], v[156:159], v[196:199], v[8:11]
	s_setprio 0
	s_barrier
; #define PG8_STAGE(bufoff, gbase, voff) do { _Pragma("unroll") for (int _i = 0; _i < 2; ++_i) \
;         __builtin_amdgcn_global_load_lds((const unsigned*)((const char*)(gbase) + (voff)[_i]), (LAS unsigned*)(lds + (bufoff) + ldsw + _i * 8192), 16, 0, 0); } while (0)
; #define PG8_LDA(dst, b, h) do { _Pragma("unroll") for (int m = 0; m < 4; ++m) _Pragma("unroll") for (int k = 0; k < 2; ++k) dst[m][k] = *(const LAS bf16x8*)(lds + PG8_SA(b, h) + aoffk[k] + m * 2048); } while (0)
; #define PG8_LDB(dst, b, h) do { _Pragma("unroll") for (int n = 0; n < 2; ++n) _Pragma("unroll") for (int k = 0; k < 2; ++k) dst[n][k] = *(const LAS bf16x8*)(lds + PG8_SB(b, h) + boffk[k] + n * 2048); } while (0)
; #define PG8_WAIT_V(n) asm volatile("s_waitcnt vmcnt(" #n ")" ::: "memory")
; #define PG8_WAIT_L(n) asm volatile("s_waitcnt lgkmcnt(" #n ")" ::: "memory")
; #define PG8_BAR __builtin_amdgcn_s_barrier()
; #define PG8_SCHED __builtin_amdgcn_sched_barrier(0)
; template <class Epi, class Sched, class GemmT>
; __device__ __forceinline__ void gemm_phase(LAS unsigned char* lds, const GemmT& g, const Sched& S, const Epi& E, const int wid) {
;     ...
;                 PG8_LDB(B0, 1, 0); PG8_LDB(B1, 1, 1); PG8_SCHED; PG8_LDA(At, 1, 0); PG8_STAGE(PG8_SA(0, 1), a2 + hA2, vA2);
;                 PG8_WAIT_V(8); PG8_WAIT_L(0); PG8_BAR; PG8_MMA(0, 0, At, B0); PG8_MMA(0, 1, At, B1); PG8_BAR; PG8_SCHED;
;                 PG8_LDA(At, 1, 1); PG8_STAGE(PG8_SB(1, 0), b3, vB2); PG8_STAGE(PG8_SB(1, 1), b3 + hB2, vB2); PG8_STAGE(PG8_SA(1, 0), a3, vA2);
;                 PG8_WAIT_V(8); PG8_WAIT_L(0); PG8_BAR; PG8_MMA(1, 0, At, B0); PG8_MMA(1, 1, At, B1); PG8_BAR; PG8_SCHED;
;             }
	s_add_i32 s80, 0, 0x18000
	s_add_i32 s82, 0, 0x1c000
	v_add_u32_e32 v64, s80, v210
	v_add_u32_e32 v132, s80, v211
	v_add_u32_e32 v144, s82, v210
	v_add_u32_e32 v148, s82, v211
	ds_read_b128 v[64:67], v64
	ds_read_b128 v[132:135], v132
	ds_read_b128 v[136:139], v234
	ds_read_b128 v[140:143], v235
	ds_read_b128 v[144:147], v144
	ds_read_b128 v[148:151], v148
	ds_read_b128 v[152:155], v236
	ds_read_b128 v[156:159], v237
	s_add_u32 s70, s70, 0x100000
	s_addc_u32 s71, s71, 0
	s_mov_b32 m0, s23
	ds_read_b128 v[160:163], v232 offset:32768
	ds_read_b128 v[164:167], v232 offset:34816
	ds_read_b128 v[168:171], v233 offset:32768
	ds_read_b128 v[172:175], v233 offset:34816
	ds_read_b128 v[188:191], v232 offset:36864
	ds_read_b128 v[192:195], v232 offset:38912
	ds_read_b128 v[196:199], v233 offset:36864
	ds_read_b128 v[200:203], v233 offset:38912
	global_load_lds_dwordx4 v176, s[70:71]
	s_mov_b32 m0, s34
	s_nop 0
	global_load_lds_dwordx4 v180, s[70:71]
	s_waitcnt vmcnt(8)
	s_waitcnt lgkmcnt(0)
	s_waitcnt lgkmcnt(0)
	v_mfma_f32_16x16x32_bf16 v[124:127], v[64:67], v[160:163], v[124:127]
	v_mfma_f32_16x16x32_bf16 v[124:127], v[132:135], v[168:171], v[124:127]
	v_mfma_f32_16x16x32_bf16 v[120:123], v[140:143], v[168:171], v[120:123]
	v_mfma_f32_16x16x32_bf16 v[120:123], v[136:139], v[160:163], v[120:123]
	s_barrier
	s_setprio 3
	v_mfma_f32_16x16x32_bf16 v[104:107], v[136:139], v[164:167], v[104:107]
	v_mfma_f32_16x16x32_bf16 v[104:107], v[140:143], v[172:175], v[104:107]
	v_mfma_f32_16x16x32_bf16 v[40:43], v[132:135], v[172:175], v[40:43]
	v_mfma_f32_16x16x32_bf16 v[40:43], v[64:67], v[164:167], v[40:43]
	v_mfma_f32_16x16x32_bf16 v[32:35], v[64:67], v[188:191], v[32:35]
	v_mfma_f32_16x16x32_bf16 v[32:35], v[132:135], v[196:199], v[32:35]
	v_mfma_f32_16x16x32_bf16 v[96:99], v[140:143], v[196:199], v[96:99]
	v_mfma_f32_16x16x32_bf16 v[96:99], v[136:139], v[188:191], v[96:99]
	v_mfma_f32_16x16x32_bf16 v[92:95], v[136:139], v[192:195], v[92:95]
	v_mfma_f32_16x16x32_bf16 v[92:95], v[140:143], v[200:203], v[92:95]
	v_mfma_f32_16x16x32_bf16 v[112:115], v[132:135], v[200:203], v[112:115]
	v_mfma_f32_16x16x32_bf16 v[112:115], v[64:67], v[192:195], v[112:115]
	s_setprio 0
	s_setprio 3
	v_mfma_f32_16x16x32_bf16 v[68:71], v[144:147], v[160:163], v[68:71]
	v_mfma_f32_16x16x32_bf16 v[68:71], v[148:151], v[168:171], v[68:71]
	v_mfma_f32_16x16x32_bf16 v[60:63], v[156:159], v[168:171], v[60:63]
	v_mfma_f32_16x16x32_bf16 v[60:63], v[152:155], v[160:163], v[60:63]
	v_mfma_f32_16x16x32_bf16 v[20:23], v[152:155], v[164:167], v[20:23]
	v_mfma_f32_16x16x32_bf16 v[20:23], v[156:159], v[172:175], v[20:23]
	v_mfma_f32_16x16x32_bf16 v[76:79], v[148:151], v[172:175], v[76:79]
	v_mfma_f32_16x16x32_bf16 v[76:79], v[144:147], v[164:167], v[76:79]
	v_mfma_f32_16x16x32_bf16 v[72:75], v[144:147], v[188:191], v[72:75]
	v_mfma_f32_16x16x32_bf16 v[72:75], v[148:151], v[196:199], v[72:75]
	v_mfma_f32_16x16x32_bf16 v[16:19], v[156:159], v[196:199], v[16:19]
	v_mfma_f32_16x16x32_bf16 v[16:19], v[152:155], v[188:191], v[16:19]
	v_mfma_f32_16x16x32_bf16 v[80:83], v[152:155], v[192:195], v[80:83]
	v_mfma_f32_16x16x32_bf16 v[80:83], v[156:159], v[200:203], v[80:83]
	v_mfma_f32_16x16x32_bf16 v[84:87], v[148:151], v[200:203], v[84:87]
	v_mfma_f32_16x16x32_bf16 v[84:87], v[144:147], v[192:195], v[84:87]
	s_setprio 0
	s_barrier
	s_add_i32 s70, s80, s68
	s_mov_b32 m0, s70
	ds_read_b128 v[160:163], v232 offset:49152
	ds_read_b128 v[164:167], v232 offset:51200
	ds_read_b128 v[168:171], v233 offset:49152
	ds_read_b128 v[172:175], v233 offset:51200
	ds_read_b128 v[188:191], v232 offset:53248
	ds_read_b128 v[192:195], v232 offset:55296
	ds_read_b128 v[196:199], v233 offset:53248
	ds_read_b128 v[200:203], v233 offset:55296
	s_add_u32 s98, s66, 0x80
	s_addc_u32 s99, s67, 0
	s_nop 0
	global_load_lds_dwordx4 v178, s[98:99]
	s_add_i32 m0, s70, 0x2000
	s_add_u32 s66, s66, 0x100080
	s_addc_u32 s67, s67, 0
	s_add_i32 s70, s82, s68
	global_load_lds_dwordx4 v182, s[98:99]
	s_mov_b32 m0, s70
	s_nop 0
	global_load_lds_dwordx4 v178, s[66:67]
	s_add_i32 m0, s70, 0x2000
	s_nop 0
	global_load_lds_dwordx4 v182, s[66:67]
	s_mov_b32 m0, s54
	s_nop 0
	global_load_lds_dwordx4 v176, s[100:101]
	s_mov_b32 m0, s55
	s_nop 0
	global_load_lds_dwordx4 v180, s[100:101]
	s_waitcnt vmcnt(8)
	s_waitcnt lgkmcnt(0)
	s_waitcnt lgkmcnt(0)
	v_mfma_f32_16x16x32_bf16 v[12:15], v[64:67], v[192:195], v[12:15]
	v_mfma_f32_16x16x32_bf16 v[56:59], v[64:67], v[160:163], v[56:59]
	v_mfma_f32_16x16x32_bf16 v[56:59], v[132:135], v[168:171], v[56:59]
	v_mfma_f32_16x16x32_bf16 v[108:111], v[136:139], v[160:163], v[108:111]
	s_barrier
	s_setprio 3
	v_mfma_f32_16x16x32_bf16 v[108:111], v[140:143], v[168:171], v[108:111]
	v_mfma_f32_16x16x32_bf16 v[36:39], v[64:67], v[164:167], v[36:39]
	v_mfma_f32_16x16x32_bf16 v[36:39], v[132:135], v[172:175], v[36:39]
	v_mfma_f32_16x16x32_bf16 v[100:103], v[136:139], v[164:167], v[100:103]
	v_mfma_f32_16x16x32_bf16 v[100:103], v[140:143], v[172:175], v[100:103]
	v_mfma_f32_16x16x32_bf16 v[28:31], v[64:67], v[188:191], v[28:31]
	v_mfma_f32_16x16x32_bf16 v[28:31], v[132:135], v[196:199], v[28:31]
	v_mfma_f32_16x16x32_bf16 v[88:91], v[136:139], v[188:191], v[88:91]
	v_mfma_f32_16x16x32_bf16 v[88:91], v[140:143], v[196:199], v[88:91]
	v_mfma_f32_16x16x32_bf16 v[64:67], v[132:135], v[200:203], v[12:15]
	v_mfma_f32_16x16x32_bf16 v[12:15], v[136:139], v[192:195], v[24:27]
	v_mfma_f32_16x16x32_bf16 v[24:27], v[140:143], v[200:203], v[12:15]
	s_setprio 0
	s_setprio 3
	v_mfma_f32_16x16x32_bf16 v[12:15], v[144:147], v[160:163], v[44:47]
	v_mfma_f32_16x16x32_bf16 v[44:47], v[148:151], v[168:171], v[12:15]
	v_mfma_f32_16x16x32_bf16 v[0:3], v[152:155], v[160:163], v[0:3]
	v_mfma_f32_16x16x32_bf16 v[0:3], v[156:159], v[168:171], v[0:3]
	v_mfma_f32_16x16x32_bf16 v[4:7], v[152:155], v[164:167], v[4:7]
	v_mfma_f32_16x16x32_bf16 v[4:7], v[156:159], v[172:175], v[4:7]
	v_mfma_f32_16x16x32_bf16 v[12:15], v[144:147], v[164:167], v[48:51]
	v_mfma_f32_16x16x32_bf16 v[48:51], v[148:151], v[172:175], v[12:15]
	v_mfma_f32_16x16x32_bf16 v[8:11], v[152:155], v[188:191], v[8:11]
	v_mfma_f32_16x16x32_bf16 v[8:11], v[156:159], v[196:199], v[8:11]
	v_mfma_f32_16x16x32_bf16 v[12:15], v[144:147], v[188:191], v[52:55]
	v_mfma_f32_16x16x32_bf16 v[52:55], v[148:151], v[196:199], v[12:15]
	v_mfma_f32_16x16x32_bf16 v[12:15], v[144:147], v[192:195], v[116:119]
	v_mfma_f32_16x16x32_bf16 v[116:119], v[148:151], v[200:203], v[12:15]
	v_mfma_f32_16x16x32_bf16 v[12:15], v[152:155], v[192:195], v[128:131]
	v_mfma_f32_16x16x32_bf16 v[128:131], v[156:159], v[200:203], v[12:15]
	s_setprio 0
	s_barrier
	s_add_i32 s81, s81, 2
	s_add_u32 s64, s64, 0x100
	s_addc_u32 s65, s65, 0
	s_add_u32 s78, s78, 0x100
	s_addc_u32 s79, s79, 0
	s_cmp_gt_u32 s81, 61
	s_cbranch_scc0 .LBB0_936
	s_and_b64 vcc, exec, s[40:41]
	s_cbranch_vccz .LBB0_939
	s_barrier

; #define PG8_STAGE(bufoff, gbase, voff) do { _Pragma("unroll") for (int _i = 0; _i < 2; ++_i) \
;         __builtin_amdgcn_global_load_lds((const unsigned*)((const char*)(gbase) + (voff)[_i]), (LAS unsigned*)(lds + (bufoff) + ldsw + _i * 8192), 16, 0, 0); } while (0)
; #define PG8_LDA(dst, b, h) do { _Pragma("unroll") for (int m = 0; m < 4; ++m) _Pragma("unroll") for (int k = 0; k < 2; ++k) dst[m][k] = *(const LAS bf16x8*)(lds + PG8_SA(b, h) + aoffk[k] + m * 2048); } while (0)
; #define PG8_LDB(dst, b, h) do { _Pragma("unroll") for (int n = 0; n < 2; ++n) _Pragma("unroll") for (int k = 0; k < 2; ++k) dst[n][k] = *(const LAS bf16x8*)(lds + PG8_SB(b, h) + boffk[k] + n * 2048); } while (0)
; #define PG8_WAIT_V(n) asm volatile("s_waitcnt vmcnt(" #n ")" ::: "memory")
; #define PG8_WAIT_L(n) asm volatile("s_waitcnt lgkmcnt(" #n ")" ::: "memory")
; #define PG8_BAR __builtin_amdgcn_s_barrier()
; #define PG8_SCHED __builtin_amdgcn_sched_barrier(0)
; template <class Epi, class Sched, class GemmT>
; __device__ __forceinline__ void gemm_phase(LAS unsigned char* lds, const GemmT& g, const Sched& S, const Epi& E, const int wid) {
;     ...
;                 PG8_LDB(B0, 0, 0); PG8_LDB(B1, 0, 1); PG8_SCHED; PG8_LDA(At, 0, 0); PG8_STAGE(PG8_SA(1, 1), a1 + hstepA, voffA);
;                 PG8_WAIT_V(8); PG8_WAIT_L(0); PG8_BAR; PG8_MMA(0, 0, At, B0); PG8_MMA(0, 1, At, B1); PG8_BAR; PG8_SCHED;
;                 PG8_LDA(At, 0, 1); PG8_STAGE(PG8_SB(0, 0), b2, vB2); PG8_STAGE(PG8_SB(0, 1), b2 + hB2, vB2); PG8_STAGE(PG8_SA(0, 0), a2, vA2);
;                 PG8_WAIT_V(8); PG8_WAIT_L(0); PG8_BAR; PG8_MMA(1, 0, At, B0); PG8_MMA(1, 1, At, B1); PG8_BAR; PG8_SCHED;
.LBB0_1096:
	ds_read_b128 v[128:131], v188
	ds_read_b128 v[132:135], v189
	ds_read_b128 v[136:139], v190
	ds_read_b128 v[140:143], v191
	ds_read_b128 v[144:147], v192
	ds_read_b128 v[148:151], v193
	ds_read_b128 v[152:155], v194
	ds_read_b128 v[156:159], v195
	s_add_u32 s24, s22, 0xffd50080
	s_addc_u32 s25, s23, -1
	s_cmpk_eq_i32 s56, 0xa8
	s_cselect_b32 s27, s19, s25
	s_cselect_b32 s26, s18, s24
	s_cselect_b32 s25, s53, s55
	s_cselect_b32 s24, s52, s54
	s_add_i32 m0, s34, 0xc000
	ds_read_b128 v[160:163], v196
	ds_read_b128 v[164:167], v196 offset:2048
	ds_read_b128 v[180:183], v197
	ds_read_b128 v[202:205], v197 offset:2048
	ds_read_b128 v[206:209], v196 offset:4096
	ds_read_b128 v[210:213], v196 offset:6144
	ds_read_b128 v[214:217], v197 offset:4096
	ds_read_b128 v[218:221], v197 offset:6144
	global_load_lds_dwordx4 v168, s[22:23]
	s_add_i32 m0, s34, 0xe000
	s_nop 0
	global_load_lds_dwordx4 v172, s[22:23]
	s_waitcnt vmcnt(8)
	s_waitcnt lgkmcnt(0)
	s_waitcnt lgkmcnt(0)
	v_mfma_f32_16x16x32_bf16 v[124:127], v[128:131], v[160:163], v[124:127]
	v_mfma_f32_16x16x32_bf16 v[124:127], v[132:135], v[180:183], v[124:127]
	v_mfma_f32_16x16x32_bf16 v[120:123], v[140:143], v[180:183], v[120:123]
	v_mfma_f32_16x16x32_bf16 v[120:123], v[136:139], v[160:163], v[120:123]
	s_barrier
	s_setprio 3
	v_mfma_f32_16x16x32_bf16 v[104:107], v[136:139], v[164:167], v[104:107]
	v_mfma_f32_16x16x32_bf16 v[104:107], v[140:143], v[202:205], v[104:107]
	v_mfma_f32_16x16x32_bf16 v[112:115], v[132:135], v[202:205], v[112:115]
	v_mfma_f32_16x16x32_bf16 v[112:115], v[128:131], v[164:167], v[112:115]
	v_mfma_f32_16x16x32_bf16 v[96:99], v[128:131], v[206:209], v[96:99]
	v_mfma_f32_16x16x32_bf16 v[96:99], v[132:135], v[214:217], v[96:99]
	v_mfma_f32_16x16x32_bf16 v[88:91], v[140:143], v[214:217], v[88:91]
	v_mfma_f32_16x16x32_bf16 v[88:91], v[136:139], v[206:209], v[88:91]
	v_mfma_f32_16x16x32_bf16 v[72:75], v[136:139], v[210:213], v[72:75]
	v_mfma_f32_16x16x32_bf16 v[72:75], v[140:143], v[218:221], v[72:75]
	v_mfma_f32_16x16x32_bf16 v[80:83], v[132:135], v[218:221], v[80:83]
	v_mfma_f32_16x16x32_bf16 v[80:83], v[128:131], v[210:213], v[80:83]
	s_setprio 0
	s_setprio 3
	v_mfma_f32_16x16x32_bf16 v[116:119], v[144:147], v[160:163], v[116:119]
	v_mfma_f32_16x16x32_bf16 v[116:119], v[148:151], v[180:183], v[116:119]
	v_mfma_f32_16x16x32_bf16 v[108:111], v[156:159], v[180:183], v[108:111]
	v_mfma_f32_16x16x32_bf16 v[108:111], v[152:155], v[160:163], v[108:111]
	v_mfma_f32_16x16x32_bf16 v[92:95], v[152:155], v[164:167], v[92:95]
	v_mfma_f32_16x16x32_bf16 v[92:95], v[156:159], v[202:205], v[92:95]
	v_mfma_f32_16x16x32_bf16 v[100:103], v[148:151], v[202:205], v[100:103]
	v_mfma_f32_16x16x32_bf16 v[100:103], v[144:147], v[164:167], v[100:103]
	v_mfma_f32_16x16x32_bf16 v[84:87], v[144:147], v[206:209], v[84:87]
	v_mfma_f32_16x16x32_bf16 v[84:87], v[148:151], v[214:217], v[84:87]
	v_mfma_f32_16x16x32_bf16 v[76:79], v[156:159], v[214:217], v[76:79]
	v_mfma_f32_16x16x32_bf16 v[76:79], v[152:155], v[206:209], v[76:79]
	v_mfma_f32_16x16x32_bf16 v[60:63], v[152:155], v[210:213], v[60:63]
	v_mfma_f32_16x16x32_bf16 v[60:63], v[156:159], v[218:221], v[60:63]
	v_mfma_f32_16x16x32_bf16 v[68:71], v[148:151], v[218:221], v[68:71]
	v_mfma_f32_16x16x32_bf16 v[68:71], v[144:147], v[210:213], v[68:71]
	s_setprio 0
	s_barrier
	s_add_i32 s57, s41, s68
	s_mov_b32 m0, s57
	ds_read_b128 v[160:163], v196 offset:16384
	ds_read_b128 v[164:167], v196 offset:18432
	ds_read_b128 v[180:183], v197 offset:16384
	ds_read_b128 v[202:205], v197 offset:18432
	ds_read_b128 v[206:209], v196 offset:20480
	ds_read_b128 v[210:213], v196 offset:22528
	ds_read_b128 v[214:217], v197 offset:20480
	ds_read_b128 v[218:221], v197 offset:22528
	global_load_lds_dwordx4 v170, s[24:25]
	s_add_i32 m0, s57, 0x2000
	s_add_u32 s58, s24, 0x2b0000
	s_addc_u32 s59, s25, 0
	s_add_i32 s57, s42, s68
	global_load_lds_dwordx4 v174, s[24:25]
	s_mov_b32 m0, s57
	s_nop 0
	global_load_lds_dwordx4 v170, s[58:59]
	s_add_i32 m0, s57, 0x2000
	s_nop 0
	global_load_lds_dwordx4 v174, s[58:59]
	s_mov_b32 m0, s34
	s_nop 0
	s_add_u32 s100, s26, 0x80
	s_addc_u32 s101, s27, 0
	global_load_lds_dwordx4 v168, s[26:27]
	s_mov_b32 m0, s35
	s_nop 0
	global_load_lds_dwordx4 v172, s[26:27]
	s_waitcnt vmcnt(8)
	s_waitcnt lgkmcnt(0)
	s_waitcnt lgkmcnt(0)
	v_mfma_f32_16x16x32_bf16 v[52:55], v[128:131], v[160:163], v[52:55]
	v_mfma_f32_16x16x32_bf16 v[52:55], v[132:135], v[180:183], v[52:55]
	v_mfma_f32_16x16x32_bf16 v[48:51], v[140:143], v[180:183], v[48:51]
	v_mfma_f32_16x16x32_bf16 v[48:51], v[136:139], v[160:163], v[48:51]
	s_barrier
	s_setprio 3
	v_mfma_f32_16x16x32_bf16 v[32:35], v[136:139], v[164:167], v[32:35]
	v_mfma_f32_16x16x32_bf16 v[32:35], v[140:143], v[202:205], v[32:35]
	v_mfma_f32_16x16x32_bf16 v[36:39], v[132:135], v[202:205], v[36:39]
	v_mfma_f32_16x16x32_bf16 v[36:39], v[128:131], v[164:167], v[36:39]
	v_mfma_f32_16x16x32_bf16 v[20:23], v[128:131], v[206:209], v[20:23]
	v_mfma_f32_16x16x32_bf16 v[20:23], v[132:135], v[214:217], v[20:23]
	v_mfma_f32_16x16x32_bf16 v[8:11], v[140:143], v[214:217], v[8:11]
	v_mfma_f32_16x16x32_bf16 v[8:11], v[136:139], v[206:209], v[8:11]
	v_mfma_f32_16x16x32_bf16 v[0:3], v[136:139], v[210:213], v[0:3]
	v_mfma_f32_16x16x32_bf16 v[0:3], v[140:143], v[218:221], v[0:3]
	v_mfma_f32_16x16x32_bf16 v[4:7], v[132:135], v[218:221], v[4:7]
	v_mfma_f32_16x16x32_bf16 v[4:7], v[128:131], v[210:213], v[4:7]
	s_setprio 0
	s_setprio 3
	v_mfma_f32_16x16x32_bf16 v[64:67], v[144:147], v[160:163], v[64:67]
	v_mfma_f32_16x16x32_bf16 v[64:67], v[148:151], v[180:183], v[64:67]
	v_mfma_f32_16x16x32_bf16 v[56:59], v[156:159], v[180:183], v[56:59]
	v_mfma_f32_16x16x32_bf16 v[56:59], v[152:155], v[160:163], v[56:59]
	v_mfma_f32_16x16x32_bf16 v[40:43], v[152:155], v[164:167], v[40:43]
	v_mfma_f32_16x16x32_bf16 v[40:43], v[156:159], v[202:205], v[40:43]
	v_mfma_f32_16x16x32_bf16 v[44:47], v[148:151], v[202:205], v[44:47]
	v_mfma_f32_16x16x32_bf16 v[44:47], v[144:147], v[164:167], v[44:47]
	v_mfma_f32_16x16x32_bf16 v[28:31], v[144:147], v[206:209], v[28:31]
	v_mfma_f32_16x16x32_bf16 v[28:31], v[148:151], v[214:217], v[28:31]
	v_mfma_f32_16x16x32_bf16 v[24:27], v[156:159], v[214:217], v[24:27]
	v_mfma_f32_16x16x32_bf16 v[24:27], v[152:155], v[206:209], v[24:27]
	v_mfma_f32_16x16x32_bf16 v[12:15], v[152:155], v[210:213], v[12:15]
	v_mfma_f32_16x16x32_bf16 v[12:15], v[156:159], v[218:221], v[12:15]
	v_mfma_f32_16x16x32_bf16 v[16:19], v[148:151], v[218:221], v[16:19]
	v_mfma_f32_16x16x32_bf16 v[16:19], v[144:147], v[210:213], v[16:19]
	s_setprio 0
	s_barrier
; #define PG8_STAGE(bufoff, gbase, voff) do { _Pragma("unroll") for (int _i = 0; _i < 2; ++_i) \
;         __builtin_amdgcn_global_load_lds((const unsigned*)((const char*)(gbase) + (voff)[_i]), (LAS unsigned*)(lds + (bufoff) + ldsw + _i * 8192), 16, 0, 0); } while (0)
; #define PG8_LDA(dst, b, h) do { _Pragma("unroll") for (int m = 0; m < 4; ++m) _Pragma("unroll") for (int k = 0; k < 2; ++k) dst[m][k] = *(const LAS bf16x8*)(lds + PG8_SA(b, h) + aoffk[k] + m * 2048); } while (0)
; #define PG8_LDB(dst, b, h) do { _Pragma("unroll") for (int n = 0; n < 2; ++n) _Pragma("unroll") for (int k = 0; k < 2; ++k) dst[n][k] = *(const LAS bf16x8*)(lds + PG8_SB(b, h) + boffk[k] + n * 2048); } while (0)
; #define PG8_WAIT_V(n) asm volatile("s_waitcnt vmcnt(" #n ")" ::: "memory")
; #define PG8_WAIT_L(n) asm volatile("s_waitcnt lgkmcnt(" #n ")" ::: "memory")
; #define PG8_BAR __builtin_amdgcn_s_barrier()
; #define PG8_SCHED __builtin_amdgcn_sched_barrier(0)
; template <class Epi, class Sched, class GemmT>
; __device__ __forceinline__ void gemm_phase(LAS unsigned char* lds, const GemmT& g, const Sched& S, const Epi& E, const int wid) {
;     ...
;                 PG8_LDB(B0, 1, 0); PG8_LDB(B1, 1, 1); PG8_SCHED; PG8_LDA(At, 1, 0); PG8_STAGE(PG8_SA(0, 1), a2 + hA2, vA2);
;                 PG8_WAIT_V(8); PG8_WAIT_L(0); PG8_BAR; PG8_MMA(0, 0, At, B0); PG8_MMA(0, 1, At, B1); PG8_BAR; PG8_SCHED;
;                 PG8_LDA(At, 1, 1); PG8_STAGE(PG8_SB(1, 0), b3, vB2); PG8_STAGE(PG8_SB(1, 1), b3 + hB2, vB2); PG8_STAGE(PG8_SA(1, 0), a3, vA2);
;                 PG8_WAIT_V(8); PG8_WAIT_L(0); PG8_BAR; PG8_MMA(1, 0, At, B0); PG8_MMA(1, 1, At, B1); PG8_BAR; PG8_SCHED;
;             }
	s_add_i32 s57, 0, 0x18000
	s_add_i32 s58, 0, 0x1c000
	v_add_u32_e32 v128, s57, v185
	v_add_u32_e32 v132, s57, v186
	v_add_u32_e32 v144, s58, v185
	v_add_u32_e32 v148, s58, v186
	ds_read_b128 v[128:131], v128
	ds_read_b128 v[132:135], v132
	ds_read_b128 v[136:139], v198
	ds_read_b128 v[140:143], v199
	ds_read_b128 v[144:147], v144
	ds_read_b128 v[148:151], v148
	ds_read_b128 v[152:155], v200
	ds_read_b128 v[156:159], v201
	s_add_u32 s26, s26, 0x2b0000
	s_addc_u32 s27, s27, 0
	s_mov_b32 m0, s36
	ds_read_b128 v[160:163], v196 offset:32768
	ds_read_b128 v[164:167], v196 offset:34816
	ds_read_b128 v[180:183], v197 offset:32768
	ds_read_b128 v[202:205], v197 offset:34816
	ds_read_b128 v[206:209], v196 offset:36864
	ds_read_b128 v[210:213], v196 offset:38912
	ds_read_b128 v[214:217], v197 offset:36864
	ds_read_b128 v[218:221], v197 offset:38912
	global_load_lds_dwordx4 v168, s[26:27]
	s_mov_b32 m0, s37
	s_nop 0
	global_load_lds_dwordx4 v172, s[26:27]
	s_waitcnt vmcnt(8)
	s_waitcnt lgkmcnt(0)
	s_waitcnt lgkmcnt(0)
	v_mfma_f32_16x16x32_bf16 v[124:127], v[128:131], v[160:163], v[124:127]
	v_mfma_f32_16x16x32_bf16 v[124:127], v[132:135], v[180:183], v[124:127]
	v_mfma_f32_16x16x32_bf16 v[120:123], v[140:143], v[180:183], v[120:123]
	v_mfma_f32_16x16x32_bf16 v[120:123], v[136:139], v[160:163], v[120:123]
	s_barrier
	s_setprio 3
	v_mfma_f32_16x16x32_bf16 v[104:107], v[136:139], v[164:167], v[104:107]
	v_mfma_f32_16x16x32_bf16 v[104:107], v[140:143], v[202:205], v[104:107]
	v_mfma_f32_16x16x32_bf16 v[112:115], v[132:135], v[202:205], v[112:115]
	v_mfma_f32_16x16x32_bf16 v[112:115], v[128:131], v[164:167], v[112:115]
	v_mfma_f32_16x16x32_bf16 v[96:99], v[128:131], v[206:209], v[96:99]
	v_mfma_f32_16x16x32_bf16 v[96:99], v[132:135], v[214:217], v[96:99]
	v_mfma_f32_16x16x32_bf16 v[88:91], v[140:143], v[214:217], v[88:91]
	v_mfma_f32_16x16x32_bf16 v[88:91], v[136:139], v[206:209], v[88:91]
	v_mfma_f32_16x16x32_bf16 v[72:75], v[136:139], v[210:213], v[72:75]
	v_mfma_f32_16x16x32_bf16 v[72:75], v[140:143], v[218:221], v[72:75]
	v_mfma_f32_16x16x32_bf16 v[80:83], v[132:135], v[218:221], v[80:83]
	v_mfma_f32_16x16x32_bf16 v[80:83], v[128:131], v[210:213], v[80:83]
	s_setprio 0
	s_setprio 3
	v_mfma_f32_16x16x32_bf16 v[116:119], v[144:147], v[160:163], v[116:119]
	v_mfma_f32_16x16x32_bf16 v[116:119], v[148:151], v[180:183], v[116:119]
	v_mfma_f32_16x16x32_bf16 v[108:111], v[156:159], v[180:183], v[108:111]
	v_mfma_f32_16x16x32_bf16 v[108:111], v[152:155], v[160:163], v[108:111]
	v_mfma_f32_16x16x32_bf16 v[92:95], v[152:155], v[164:167], v[92:95]
	v_mfma_f32_16x16x32_bf16 v[92:95], v[156:159], v[202:205], v[92:95]
	v_mfma_f32_16x16x32_bf16 v[100:103], v[148:151], v[202:205], v[100:103]
	v_mfma_f32_16x16x32_bf16 v[100:103], v[144:147], v[164:167], v[100:103]
	v_mfma_f32_16x16x32_bf16 v[84:87], v[144:147], v[206:209], v[84:87]
	v_mfma_f32_16x16x32_bf16 v[84:87], v[148:151], v[214:217], v[84:87]
	v_mfma_f32_16x16x32_bf16 v[76:79], v[156:159], v[214:217], v[76:79]
	v_mfma_f32_16x16x32_bf16 v[76:79], v[152:155], v[206:209], v[76:79]
	v_mfma_f32_16x16x32_bf16 v[60:63], v[152:155], v[210:213], v[60:63]
	v_mfma_f32_16x16x32_bf16 v[60:63], v[156:159], v[218:221], v[60:63]
	v_mfma_f32_16x16x32_bf16 v[68:71], v[148:151], v[218:221], v[68:71]
	v_mfma_f32_16x16x32_bf16 v[68:71], v[144:147], v[210:213], v[68:71]
	s_setprio 0
	s_barrier
	s_add_i32 s26, s57, s68
	s_mov_b32 m0, s26
	ds_read_b128 v[160:163], v196 offset:49152
	ds_read_b128 v[164:167], v196 offset:51200
	ds_read_b128 v[180:183], v197 offset:49152
	ds_read_b128 v[202:205], v197 offset:51200
	ds_read_b128 v[206:209], v196 offset:53248
	ds_read_b128 v[210:213], v196 offset:55296
	ds_read_b128 v[214:217], v197 offset:53248
	ds_read_b128 v[218:221], v197 offset:55296
	s_add_u32 s98, s24, 0x80
	s_addc_u32 s99, s25, 0
	s_nop 0
	global_load_lds_dwordx4 v170, s[98:99]
	s_add_i32 m0, s26, 0x2000
	s_add_u32 s24, s24, 0x2b0080
	s_addc_u32 s25, s25, 0
	s_add_i32 s26, s58, s68
	global_load_lds_dwordx4 v174, s[98:99]
	s_mov_b32 m0, s26
	s_nop 0
	global_load_lds_dwordx4 v170, s[24:25]
	s_add_i32 m0, s26, 0x2000
	s_nop 0
	global_load_lds_dwordx4 v174, s[24:25]
	s_mov_b32 m0, s39
	s_nop 0
	global_load_lds_dwordx4 v168, s[100:101]
	s_mov_b32 m0, s40
	s_nop 0
	global_load_lds_dwordx4 v172, s[100:101]
	s_waitcnt vmcnt(8)
	s_waitcnt lgkmcnt(0)
	s_waitcnt lgkmcnt(0)
	v_mfma_f32_16x16x32_bf16 v[52:55], v[128:131], v[160:163], v[52:55]
	v_mfma_f32_16x16x32_bf16 v[52:55], v[132:135], v[180:183], v[52:55]
	v_mfma_f32_16x16x32_bf16 v[48:51], v[140:143], v[180:183], v[48:51]
	v_mfma_f32_16x16x32_bf16 v[48:51], v[136:139], v[160:163], v[48:51]
	s_barrier
	s_setprio 3
	v_mfma_f32_16x16x32_bf16 v[32:35], v[136:139], v[164:167], v[32:35]
	v_mfma_f32_16x16x32_bf16 v[32:35], v[140:143], v[202:205], v[32:35]
	v_mfma_f32_16x16x32_bf16 v[36:39], v[132:135], v[202:205], v[36:39]
	v_mfma_f32_16x16x32_bf16 v[36:39], v[128:131], v[164:167], v[36:39]
	v_mfma_f32_16x16x32_bf16 v[20:23], v[128:131], v[206:209], v[20:23]
	v_mfma_f32_16x16x32_bf16 v[20:23], v[132:135], v[214:217], v[20:23]
	v_mfma_f32_16x16x32_bf16 v[8:11], v[140:143], v[214:217], v[8:11]
	v_mfma_f32_16x16x32_bf16 v[8:11], v[136:139], v[206:209], v[8:11]
	v_mfma_f32_16x16x32_bf16 v[0:3], v[136:139], v[210:213], v[0:3]
	v_mfma_f32_16x16x32_bf16 v[0:3], v[140:143], v[218:221], v[0:3]
	v_mfma_f32_16x16x32_bf16 v[4:7], v[132:135], v[218:221], v[4:7]
	v_mfma_f32_16x16x32_bf16 v[4:7], v[128:131], v[210:213], v[4:7]
	s_setprio 0
	s_setprio 3
	v_mfma_f32_16x16x32_bf16 v[64:67], v[144:147], v[160:163], v[64:67]
	v_mfma_f32_16x16x32_bf16 v[64:67], v[148:151], v[180:183], v[64:67]
	v_mfma_f32_16x16x32_bf16 v[56:59], v[156:159], v[180:183], v[56:59]
	v_mfma_f32_16x16x32_bf16 v[56:59], v[152:155], v[160:163], v[56:59]
	v_mfma_f32_16x16x32_bf16 v[40:43], v[152:155], v[164:167], v[40:43]
	v_mfma_f32_16x16x32_bf16 v[40:43], v[156:159], v[202:205], v[40:43]
	v_mfma_f32_16x16x32_bf16 v[44:47], v[148:151], v[202:205], v[44:47]
	v_mfma_f32_16x16x32_bf16 v[44:47], v[144:147], v[164:167], v[44:47]
	v_mfma_f32_16x16x32_bf16 v[28:31], v[144:147], v[206:209], v[28:31]
	v_mfma_f32_16x16x32_bf16 v[28:31], v[148:151], v[214:217], v[28:31]
	v_mfma_f32_16x16x32_bf16 v[24:27], v[156:159], v[214:217], v[24:27]
	v_mfma_f32_16x16x32_bf16 v[24:27], v[152:155], v[206:209], v[24:27]
	v_mfma_f32_16x16x32_bf16 v[12:15], v[152:155], v[210:213], v[12:15]
	v_mfma_f32_16x16x32_bf16 v[12:15], v[156:159], v[218:221], v[12:15]
	v_mfma_f32_16x16x32_bf16 v[16:19], v[148:151], v[218:221], v[16:19]
	v_mfma_f32_16x16x32_bf16 v[16:19], v[144:147], v[210:213], v[16:19]
	s_setprio 0
	s_barrier
	s_add_i32 s56, s56, 2
	s_add_u32 s22, s22, 0x100
	s_addc_u32 s23, s23, 0
	s_add_u32 s54, s54, 0x100
	s_addc_u32 s55, s55, 0
	s_cmpk_gt_u32 s56, 0xa9
	s_cbranch_scc0 .LBB0_1096
	s_and_b64 vcc, exec, s[8:9]
	s_cbranch_vccz .LBB0_1099
	s_barrier
